# v61 + back-edge rotation in the four GEMM K-loops: loop-carried s_mov, next-iteration SALU address block and exit test moved in front of the loop-back barrier
# baseline (speedup 1.0000x reference)
; #define PG8_STAGE(bufoff, gbase, voff) do { _Pragma("unroll") for (int _i = 0; _i < 2; ++_i) \
;         __builtin_amdgcn_global_load_lds((const unsigned*)((const char*)(gbase) + (voff)[_i]), (LAS unsigned*)(lds + (bufoff) + ldsw + _i * 8192), 16, 0, 0); } while (0)
; #define PG8_LDA(dst, b, h) do { _Pragma("unroll") for (int m = 0; m < 4; ++m) _Pragma("unroll") for (int k = 0; k < 2; ++k) dst[m][k] = *(const LAS bf16x8*)(lds + PG8_SA(b, h) + aoff + m * 2048 + k * 1024); } while (0)
; #define PG8_LDB(dst, b, h) do { _Pragma("unroll") for (int n = 0; n < 2; ++n) _Pragma("unroll") for (int k = 0; k < 2; ++k) dst[n][k] = *(const LAS bf16x8*)(lds + PG8_SB(b, h) + boff + n * 2048 + k * 1024); } while (0)
; #define PG8_MMA(ai, bj, At, Bt) do { __builtin_amdgcn_s_setprio(1); _Pragma("unroll") for (int m = 0; m < 4; ++m) _Pragma("unroll") for (int n = 0; n < 2; ++n) _Pragma("unroll") for (int k = 0; k < 2; ++k) \
;         acc[ai][bj][m][n] = __builtin_amdgcn_mfma_f32_16x16x32_bf16(Bt[n][k], At[m][k], acc[ai][bj][m][n], 0, 0, 0); __builtin_amdgcn_s_setprio(0); } while (0)
; #define PG8_WAIT_V(n) asm volatile("s_waitcnt vmcnt(" #n ")" ::: "memory")
; #define PG8_WAIT_L(n) asm volatile("s_waitcnt lgkmcnt(" #n ")" ::: "memory")
; #define PG8_BAR __builtin_amdgcn_s_barrier()
; #define PG8_SCHED __builtin_amdgcn_sched_barrier(0)
; template <class Epi, class Sched>
; __device__ __forceinline__ void gemm_phase(LAS unsigned char* lds, const Gemm g, const Sched& S, const Epi& E) {
;     ...
;             PG8_LDB(B0, 0, 0); PG8_LDB(B1, 0, 1); PG8_SCHED; PG8_LDA(At, 0, 0); PG8_STAGE(PG8_SA(1, 1), a1 + hstep, voffA);
;             PG8_WAIT_V(8); PG8_WAIT_L(0); PG8_BAR; PG8_MMA(0, 0, At, B0); PG8_MMA(0, 1, At, B1); PG8_BAR; PG8_SCHED;
;             PG8_LDA(At, 0, 1); PG8_STAGE(PG8_SB(0, 0), b2, voffB); PG8_STAGE(PG8_SB(0, 1), b2 + hstep, voffB); PG8_STAGE(PG8_SA(0, 0), a2, voffA);
;             PG8_WAIT_V(8); PG8_WAIT_L(0); PG8_BAR; PG8_MMA(1, 0, At, B0); PG8_MMA(1, 1, At, B1); PG8_BAR; PG8_SCHED;
.Lrot_z:
	v_add_u32_e32 v156, s1, v142
	v_add_u32_e32 v172, s59, v142
	ds_read_b128 v[144:147], v156
	ds_read_b128 v[148:151], v156 offset:1024
	ds_read_b128 v[152:155], v156 offset:2048
	ds_read_b128 v[156:159], v156 offset:3072
	ds_read_b128 v[160:163], v172
	ds_read_b128 v[164:167], v172 offset:1024
	ds_read_b128 v[168:171], v172 offset:2048
	ds_read_b128 v[172:175], v172 offset:3072
	s_add_u32 s46, s46, s2
	s_addc_u32 s47, s47, s3
	s_add_u32 s46, s46, s20
	s_addc_u32 s47, s47, s21
	s_add_u32 s46, s46, 0x80
	s_addc_u32 s47, s47, 0
	s_add_i32 m0, s5, 0xc000
	ds_read_b128 v[176:179], v143
	ds_read_b128 v[180:183], v143 offset:1024
	ds_read_b128 v[184:187], v143 offset:2048
	ds_read_b128 v[192:195], v143 offset:3072
	ds_read_b128 v[196:199], v143 offset:4096
	ds_read_b128 v[200:203], v143 offset:5120
	ds_read_b128 v[204:207], v143 offset:6144
	ds_read_b128 v[208:211], v143 offset:7168
	global_load_lds_dwordx4 v134, s[46:47]
	s_add_i32 m0, s5, 0xe000
	s_nop 0
	global_load_lds_dwordx4 v132, s[46:47]
	s_waitcnt vmcnt(8)
	s_waitcnt lgkmcnt(0)
	s_barrier
	s_setprio 1
	s_waitcnt lgkmcnt(0)
	v_mfma_f32_16x16x32_bf16 v[122:125], v[144:147], v[176:179], v[122:125]
	v_mfma_f32_16x16x32_bf16 v[126:129], v[152:155], v[176:179], v[126:129]
	v_mfma_f32_16x16x32_bf16 v[110:113], v[144:147], v[184:187], v[110:113]
	v_mfma_f32_16x16x32_bf16 v[106:109], v[152:155], v[184:187], v[106:109]
	v_mfma_f32_16x16x32_bf16 v[94:97], v[144:147], v[196:199], v[94:97]
	v_mfma_f32_16x16x32_bf16 v[90:93], v[152:155], v[196:199], v[90:93]
	v_mfma_f32_16x16x32_bf16 v[78:81], v[144:147], v[204:207], v[78:81]
	v_mfma_f32_16x16x32_bf16 v[74:77], v[152:155], v[204:207], v[74:77]
	v_mfma_f32_16x16x32_bf16 v[122:125], v[148:151], v[180:183], v[122:125]
	v_mfma_f32_16x16x32_bf16 v[126:129], v[156:159], v[180:183], v[126:129]
	v_mfma_f32_16x16x32_bf16 v[110:113], v[148:151], v[192:195], v[110:113]
	v_mfma_f32_16x16x32_bf16 v[106:109], v[156:159], v[192:195], v[106:109]
	v_mfma_f32_16x16x32_bf16 v[94:97], v[148:151], v[200:203], v[94:97]
	v_mfma_f32_16x16x32_bf16 v[90:93], v[156:159], v[200:203], v[90:93]
	v_mfma_f32_16x16x32_bf16 v[78:81], v[148:151], v[208:211], v[78:81]
	v_mfma_f32_16x16x32_bf16 v[74:77], v[156:159], v[208:211], v[74:77]
	s_setprio 0
	s_setprio 1
	v_mfma_f32_16x16x32_bf16 v[118:121], v[160:163], v[176:179], v[118:121]
	v_mfma_f32_16x16x32_bf16 v[114:117], v[168:171], v[176:179], v[114:117]
	v_mfma_f32_16x16x32_bf16 v[102:105], v[160:163], v[184:187], v[102:105]
	v_mfma_f32_16x16x32_bf16 v[98:101], v[168:171], v[184:187], v[98:101]
	v_mfma_f32_16x16x32_bf16 v[86:89], v[160:163], v[196:199], v[86:89]
	v_mfma_f32_16x16x32_bf16 v[82:85], v[168:171], v[196:199], v[82:85]
	v_mfma_f32_16x16x32_bf16 v[70:73], v[160:163], v[204:207], v[70:73]
	v_mfma_f32_16x16x32_bf16 v[66:69], v[168:171], v[204:207], v[66:69]
	v_mfma_f32_16x16x32_bf16 v[118:121], v[164:167], v[180:183], v[118:121]
	v_mfma_f32_16x16x32_bf16 v[114:117], v[172:175], v[180:183], v[114:117]
	v_mfma_f32_16x16x32_bf16 v[102:105], v[164:167], v[192:195], v[102:105]
	v_mfma_f32_16x16x32_bf16 v[98:101], v[172:175], v[192:195], v[98:101]
	v_mfma_f32_16x16x32_bf16 v[86:89], v[164:167], v[200:203], v[86:89]
	v_mfma_f32_16x16x32_bf16 v[82:85], v[172:175], v[200:203], v[82:85]
	v_mfma_f32_16x16x32_bf16 v[70:73], v[164:167], v[208:211], v[70:73]
	v_mfma_f32_16x16x32_bf16 v[66:69], v[172:175], v[208:211], v[66:69]
	s_setprio 0
	s_barrier
	s_add_i32 s1, s1, s4
	s_mov_b32 m0, s1
	ds_read_b128 v[176:179], v143 offset:16384
	ds_read_b128 v[180:183], v143 offset:17408
	ds_read_b128 v[184:187], v143 offset:18432
	ds_read_b128 v[192:195], v143 offset:19456
	ds_read_b128 v[196:199], v143 offset:20480
	ds_read_b128 v[200:203], v143 offset:21504
	ds_read_b128 v[204:207], v143 offset:22528
	ds_read_b128 v[208:211], v143 offset:23552
	global_load_lds_dwordx4 v0, s[60:61]
	s_add_i32 m0, s1, 0x2000
	s_add_u32 s46, s60, s20
	s_addc_u32 s47, s61, s21
	s_add_i32 s1, s59, s4
	global_load_lds_dwordx4 v130, s[60:61]
	s_mov_b32 m0, s1
	s_nop 0
	global_load_lds_dwordx4 v0, s[46:47]
	s_add_i32 m0, s1, 0x2000
	s_nop 0
	global_load_lds_dwordx4 v130, s[46:47]
	s_mov_b32 m0, s5
	s_nop 0
	global_load_lds_dwordx4 v134, s[50:51]
	s_mov_b32 m0, s18
	s_nop 0
	global_load_lds_dwordx4 v132, s[50:51]
	s_waitcnt vmcnt(8)
	s_waitcnt lgkmcnt(0)
	s_barrier
	s_setprio 1
	s_waitcnt lgkmcnt(0)
	v_mfma_f32_16x16x32_bf16 v[62:65], v[144:147], v[176:179], v[62:65]
	v_mfma_f32_16x16x32_bf16 v[58:61], v[152:155], v[176:179], v[58:61]
	v_mfma_f32_16x16x32_bf16 v[46:49], v[144:147], v[184:187], v[46:49]
	v_mfma_f32_16x16x32_bf16 v[42:45], v[152:155], v[184:187], v[42:45]
	v_mfma_f32_16x16x32_bf16 v[30:33], v[144:147], v[196:199], v[30:33]
	v_mfma_f32_16x16x32_bf16 v[26:29], v[152:155], v[196:199], v[26:29]
	v_mfma_f32_16x16x32_bf16 v[14:17], v[144:147], v[204:207], v[14:17]
	v_mfma_f32_16x16x32_bf16 v[10:13], v[152:155], v[204:207], v[10:13]
	v_mfma_f32_16x16x32_bf16 v[62:65], v[148:151], v[180:183], v[62:65]
	v_mfma_f32_16x16x32_bf16 v[58:61], v[156:159], v[180:183], v[58:61]
	v_mfma_f32_16x16x32_bf16 v[46:49], v[148:151], v[192:195], v[46:49]
	v_mfma_f32_16x16x32_bf16 v[42:45], v[156:159], v[192:195], v[42:45]
	v_mfma_f32_16x16x32_bf16 v[30:33], v[148:151], v[200:203], v[30:33]
	v_mfma_f32_16x16x32_bf16 v[26:29], v[156:159], v[200:203], v[26:29]
	v_mfma_f32_16x16x32_bf16 v[14:17], v[148:151], v[208:211], v[14:17]
	v_mfma_f32_16x16x32_bf16 v[10:13], v[156:159], v[208:211], v[10:13]
	s_setprio 0
	s_setprio 1
	v_mfma_f32_16x16x32_bf16 v[54:57], v[160:163], v[176:179], v[54:57]
	v_mfma_f32_16x16x32_bf16 v[50:53], v[168:171], v[176:179], v[50:53]
	v_mfma_f32_16x16x32_bf16 v[38:41], v[160:163], v[184:187], v[38:41]
	v_mfma_f32_16x16x32_bf16 v[34:37], v[168:171], v[184:187], v[34:37]
	v_mfma_f32_16x16x32_bf16 v[22:25], v[160:163], v[196:199], v[22:25]
	v_mfma_f32_16x16x32_bf16 v[18:21], v[168:171], v[196:199], v[18:21]
	v_mfma_f32_16x16x32_bf16 v[6:9], v[160:163], v[204:207], v[6:9]
	v_mfma_f32_16x16x32_bf16 v[2:5], v[168:171], v[204:207], v[2:5]
	v_mfma_f32_16x16x32_bf16 v[54:57], v[164:167], v[180:183], v[54:57]
	v_mfma_f32_16x16x32_bf16 v[50:53], v[172:175], v[180:183], v[50:53]
	v_mfma_f32_16x16x32_bf16 v[38:41], v[164:167], v[192:195], v[38:41]
	v_mfma_f32_16x16x32_bf16 v[34:37], v[172:175], v[192:195], v[34:37]
	v_mfma_f32_16x16x32_bf16 v[22:25], v[164:167], v[200:203], v[22:25]
	v_mfma_f32_16x16x32_bf16 v[18:21], v[172:175], v[200:203], v[18:21]
	v_mfma_f32_16x16x32_bf16 v[6:9], v[164:167], v[208:211], v[6:9]
	v_mfma_f32_16x16x32_bf16 v[2:5], v[172:175], v[208:211], v[2:5]
	s_setprio 0
	s_barrier
; #define PG8_STAGE(bufoff, gbase, voff) do { _Pragma("unroll") for (int _i = 0; _i < 2; ++_i) \
;         __builtin_amdgcn_global_load_lds((const unsigned*)((const char*)(gbase) + (voff)[_i]), (LAS unsigned*)(lds + (bufoff) + ldsw + _i * 8192), 16, 0, 0); } while (0)
; #define PG8_LDA(dst, b, h) do { _Pragma("unroll") for (int m = 0; m < 4; ++m) _Pragma("unroll") for (int k = 0; k < 2; ++k) dst[m][k] = *(const LAS bf16x8*)(lds + PG8_SA(b, h) + aoff + m * 2048 + k * 1024); } while (0)
; #define PG8_LDB(dst, b, h) do { _Pragma("unroll") for (int n = 0; n < 2; ++n) _Pragma("unroll") for (int k = 0; k < 2; ++k) dst[n][k] = *(const LAS bf16x8*)(lds + PG8_SB(b, h) + boff + n * 2048 + k * 1024); } while (0)
; #define PG8_MMA(ai, bj, At, Bt) do { __builtin_amdgcn_s_setprio(1); _Pragma("unroll") for (int m = 0; m < 4; ++m) _Pragma("unroll") for (int n = 0; n < 2; ++n) _Pragma("unroll") for (int k = 0; k < 2; ++k) \
;         acc[ai][bj][m][n] = __builtin_amdgcn_mfma_f32_16x16x32_bf16(Bt[n][k], At[m][k], acc[ai][bj][m][n], 0, 0, 0); __builtin_amdgcn_s_setprio(0); } while (0)
; #define PG8_WAIT_V(n) asm volatile("s_waitcnt vmcnt(" #n ")" ::: "memory")
; #define PG8_WAIT_L(n) asm volatile("s_waitcnt lgkmcnt(" #n ")" ::: "memory")
; #define PG8_BAR __builtin_amdgcn_s_barrier()
; #define PG8_SCHED __builtin_amdgcn_sched_barrier(0)
; template <class Epi, class Sched>
; __device__ __forceinline__ void gemm_phase(LAS unsigned char* lds, const Gemm g, const Sched& S, const Epi& E) {
;     ...
;             PG8_LDB(B0, 1, 0); PG8_LDB(B1, 1, 1); PG8_SCHED; PG8_LDA(At, 1, 0); PG8_STAGE(PG8_SA(0, 1), a2 + hstep, voffA);
;             PG8_WAIT_V(8); PG8_WAIT_L(0); PG8_BAR; PG8_MMA(0, 0, At, B0); PG8_MMA(0, 1, At, B1); PG8_BAR; PG8_SCHED;
	s_add_i32 s1, 0, 0x18000
	s_add_i32 s59, 0, 0x1c000
	v_add_u32_e32 v156, s1, v142
	v_add_u32_e32 v172, s59, v142
	ds_read_b128 v[144:147], v156
	ds_read_b128 v[148:151], v156 offset:1024
	ds_read_b128 v[152:155], v156 offset:2048
	ds_read_b128 v[156:159], v156 offset:3072
	ds_read_b128 v[160:163], v172
	ds_read_b128 v[164:167], v172 offset:1024
	ds_read_b128 v[168:171], v172 offset:2048
	ds_read_b128 v[172:175], v172 offset:3072
	s_add_u32 s46, s50, s20
	s_addc_u32 s47, s51, s21
	s_mov_b32 m0, s19
	ds_read_b128 v[176:179], v143 offset:32768
	ds_read_b128 v[180:183], v143 offset:33792
	ds_read_b128 v[184:187], v143 offset:34816
	ds_read_b128 v[192:195], v143 offset:35840
	ds_read_b128 v[196:199], v143 offset:36864
	ds_read_b128 v[200:203], v143 offset:37888
	ds_read_b128 v[204:207], v143 offset:38912
	ds_read_b128 v[208:211], v143 offset:39936
	global_load_lds_dwordx4 v134, s[46:47]
	s_mov_b32 m0, s52
	s_nop 0
	global_load_lds_dwordx4 v132, s[46:47]
	s_waitcnt vmcnt(8)
	s_waitcnt lgkmcnt(0)
	s_barrier
	s_setprio 1
	s_waitcnt lgkmcnt(0)
	v_mfma_f32_16x16x32_bf16 v[122:125], v[144:147], v[176:179], v[122:125]
	v_mfma_f32_16x16x32_bf16 v[126:129], v[152:155], v[176:179], v[126:129]
	v_mfma_f32_16x16x32_bf16 v[110:113], v[144:147], v[184:187], v[110:113]
	v_mfma_f32_16x16x32_bf16 v[106:109], v[152:155], v[184:187], v[106:109]
	v_mfma_f32_16x16x32_bf16 v[94:97], v[144:147], v[196:199], v[94:97]
	v_mfma_f32_16x16x32_bf16 v[90:93], v[152:155], v[196:199], v[90:93]
	v_mfma_f32_16x16x32_bf16 v[78:81], v[144:147], v[204:207], v[78:81]
	v_mfma_f32_16x16x32_bf16 v[74:77], v[152:155], v[204:207], v[74:77]
	v_mfma_f32_16x16x32_bf16 v[122:125], v[148:151], v[180:183], v[122:125]
	v_mfma_f32_16x16x32_bf16 v[126:129], v[156:159], v[180:183], v[126:129]
	v_mfma_f32_16x16x32_bf16 v[110:113], v[148:151], v[192:195], v[110:113]
	v_mfma_f32_16x16x32_bf16 v[106:109], v[156:159], v[192:195], v[106:109]
	v_mfma_f32_16x16x32_bf16 v[94:97], v[148:151], v[200:203], v[94:97]
	v_mfma_f32_16x16x32_bf16 v[90:93], v[156:159], v[200:203], v[90:93]
	v_mfma_f32_16x16x32_bf16 v[78:81], v[148:151], v[208:211], v[78:81]
	v_mfma_f32_16x16x32_bf16 v[74:77], v[156:159], v[208:211], v[74:77]
	s_setprio 0
	s_setprio 1
	v_mfma_f32_16x16x32_bf16 v[118:121], v[160:163], v[176:179], v[118:121]
	v_mfma_f32_16x16x32_bf16 v[114:117], v[168:171], v[176:179], v[114:117]
	v_mfma_f32_16x16x32_bf16 v[102:105], v[160:163], v[184:187], v[102:105]
	v_mfma_f32_16x16x32_bf16 v[98:101], v[168:171], v[184:187], v[98:101]
	v_mfma_f32_16x16x32_bf16 v[86:89], v[160:163], v[196:199], v[86:89]
	v_mfma_f32_16x16x32_bf16 v[82:85], v[168:171], v[196:199], v[82:85]
	v_mfma_f32_16x16x32_bf16 v[70:73], v[160:163], v[204:207], v[70:73]
	v_mfma_f32_16x16x32_bf16 v[66:69], v[168:171], v[204:207], v[66:69]
	v_mfma_f32_16x16x32_bf16 v[118:121], v[164:167], v[180:183], v[118:121]
	v_mfma_f32_16x16x32_bf16 v[114:117], v[172:175], v[180:183], v[114:117]
	v_mfma_f32_16x16x32_bf16 v[102:105], v[164:167], v[192:195], v[102:105]
	v_mfma_f32_16x16x32_bf16 v[98:101], v[172:175], v[192:195], v[98:101]
	v_mfma_f32_16x16x32_bf16 v[86:89], v[164:167], v[200:203], v[86:89]
	v_mfma_f32_16x16x32_bf16 v[82:85], v[172:175], v[200:203], v[82:85]
	v_mfma_f32_16x16x32_bf16 v[70:73], v[164:167], v[208:211], v[70:73]
	v_mfma_f32_16x16x32_bf16 v[66:69], v[172:175], v[208:211], v[66:69]
	s_setprio 0
	s_barrier
; #define PG8_STAGE(bufoff, gbase, voff) do { _Pragma("unroll") for (int _i = 0; _i < 2; ++_i) \
;         __builtin_amdgcn_global_load_lds((const unsigned*)((const char*)(gbase) + (voff)[_i]), (LAS unsigned*)(lds + (bufoff) + ldsw + _i * 8192), 16, 0, 0); } while (0)
; #define PG8_LDA(dst, b, h) do { _Pragma("unroll") for (int m = 0; m < 4; ++m) _Pragma("unroll") for (int k = 0; k < 2; ++k) dst[m][k] = *(const LAS bf16x8*)(lds + PG8_SA(b, h) + aoff + m * 2048 + k * 1024); } while (0)
; #define PG8_MMA(ai, bj, At, Bt) do { __builtin_amdgcn_s_setprio(1); _Pragma("unroll") for (int m = 0; m < 4; ++m) _Pragma("unroll") for (int n = 0; n < 2; ++n) _Pragma("unroll") for (int k = 0; k < 2; ++k) \
;         acc[ai][bj][m][n] = __builtin_amdgcn_mfma_f32_16x16x32_bf16(Bt[n][k], At[m][k], acc[ai][bj][m][n], 0, 0, 0); __builtin_amdgcn_s_setprio(0); } while (0)
; #define PG8_WAIT_V(n) asm volatile("s_waitcnt vmcnt(" #n ")" ::: "memory")
; #define PG8_WAIT_L(n) asm volatile("s_waitcnt lgkmcnt(" #n ")" ::: "memory")
; #define PG8_BAR __builtin_amdgcn_s_barrier()
; #define PG8_SCHED __builtin_amdgcn_sched_barrier(0)
; template <class Epi, class Sched>
; __device__ __forceinline__ void gemm_phase(LAS unsigned char* lds, const Gemm g, const Sched& S, const Epi& E) {
;     ...
;         for (int t = 0; t < nt; t += 2) {
;             const bool last = (t == nt - 2);
;             const char* a1 = cA + (size_t)(t + 1) * kstep;
;             const char* a2 = last ? nA : cA + (size_t)(t + 2) * kstep; const char* b2 = last ? nB : cB + (size_t)(t + 2) * kstep;
;     ...
;             PG8_LDA(At, 1, 1); PG8_STAGE(PG8_SB(1, 0), b3, voffB); PG8_STAGE(PG8_SB(1, 1), b3 + hstep, voffB); PG8_STAGE(PG8_SA(1, 0), a3, voffA);
;             PG8_WAIT_V(8); PG8_WAIT_L(0); PG8_BAR; PG8_MMA(1, 0, At, B0); PG8_MMA(1, 1, At, B1); PG8_BAR; PG8_SCHED;
;         }
	s_add_i32 s1, s1, s4
	s_add_u32 s46, s60, 0x80
	s_addc_u32 s47, s61, 0
	s_mov_b32 m0, s1
	ds_read_b128 v[176:179], v143 offset:49152
	ds_read_b128 v[180:183], v143 offset:50176
	ds_read_b128 v[184:187], v143 offset:51200
	ds_read_b128 v[192:195], v143 offset:52224
	ds_read_b128 v[196:199], v143 offset:53248
	ds_read_b128 v[200:203], v143 offset:54272
	ds_read_b128 v[204:207], v143 offset:55296
	ds_read_b128 v[208:211], v143 offset:56320
	global_load_lds_dwordx4 v0, s[46:47]
	s_add_i32 m0, s1, 0x2000
	s_add_i32 s1, s59, s4
	global_load_lds_dwordx4 v130, s[46:47]
	s_add_u32 s46, s46, s20
	s_addc_u32 s47, s47, s21
	s_mov_b32 m0, s1
	s_nop 0
	global_load_lds_dwordx4 v0, s[46:47]
	s_add_i32 m0, s1, 0x2000
	s_nop 0
	global_load_lds_dwordx4 v130, s[46:47]
	s_add_u32 s46, s50, 0x80
	s_addc_u32 s47, s51, 0
	s_mov_b32 m0, s53
	s_nop 0
	global_load_lds_dwordx4 v134, s[46:47]
	s_mov_b32 m0, s54
	s_nop 0
	global_load_lds_dwordx4 v132, s[46:47]
	s_waitcnt vmcnt(8)
	s_waitcnt lgkmcnt(0)
	s_barrier
	s_setprio 1
	s_waitcnt lgkmcnt(0)
	v_mfma_f32_16x16x32_bf16 v[62:65], v[144:147], v[176:179], v[62:65]
	v_mfma_f32_16x16x32_bf16 v[58:61], v[152:155], v[176:179], v[58:61]
	v_mfma_f32_16x16x32_bf16 v[46:49], v[144:147], v[184:187], v[46:49]
	v_mfma_f32_16x16x32_bf16 v[42:45], v[152:155], v[184:187], v[42:45]
	v_mfma_f32_16x16x32_bf16 v[30:33], v[144:147], v[196:199], v[30:33]
	v_mfma_f32_16x16x32_bf16 v[26:29], v[152:155], v[196:199], v[26:29]
	v_mfma_f32_16x16x32_bf16 v[14:17], v[144:147], v[204:207], v[14:17]
	v_mfma_f32_16x16x32_bf16 v[10:13], v[152:155], v[204:207], v[10:13]
	v_mfma_f32_16x16x32_bf16 v[62:65], v[148:151], v[180:183], v[62:65]
	v_mfma_f32_16x16x32_bf16 v[58:61], v[156:159], v[180:183], v[58:61]
	v_mfma_f32_16x16x32_bf16 v[46:49], v[148:151], v[192:195], v[46:49]
	v_mfma_f32_16x16x32_bf16 v[42:45], v[156:159], v[192:195], v[42:45]
	v_mfma_f32_16x16x32_bf16 v[30:33], v[148:151], v[200:203], v[30:33]
	v_mfma_f32_16x16x32_bf16 v[26:29], v[156:159], v[200:203], v[26:29]
	v_mfma_f32_16x16x32_bf16 v[14:17], v[148:151], v[208:211], v[14:17]
	v_mfma_f32_16x16x32_bf16 v[10:13], v[156:159], v[208:211], v[10:13]
	s_setprio 0
	s_setprio 1
	v_mfma_f32_16x16x32_bf16 v[54:57], v[160:163], v[176:179], v[54:57]
	v_mfma_f32_16x16x32_bf16 v[50:53], v[168:171], v[176:179], v[50:53]
	v_mfma_f32_16x16x32_bf16 v[38:41], v[160:163], v[184:187], v[38:41]
	v_mfma_f32_16x16x32_bf16 v[34:37], v[168:171], v[184:187], v[34:37]
	v_mfma_f32_16x16x32_bf16 v[22:25], v[160:163], v[196:199], v[22:25]
	v_mfma_f32_16x16x32_bf16 v[18:21], v[168:171], v[196:199], v[18:21]
	v_mfma_f32_16x16x32_bf16 v[6:9], v[160:163], v[204:207], v[6:9]
	v_mfma_f32_16x16x32_bf16 v[2:5], v[168:171], v[204:207], v[2:5]
	v_mfma_f32_16x16x32_bf16 v[54:57], v[164:167], v[180:183], v[54:57]
	v_mfma_f32_16x16x32_bf16 v[50:53], v[172:175], v[180:183], v[50:53]
	v_mfma_f32_16x16x32_bf16 v[38:41], v[164:167], v[192:195], v[38:41]
	v_mfma_f32_16x16x32_bf16 v[34:37], v[172:175], v[192:195], v[34:37]
	v_mfma_f32_16x16x32_bf16 v[22:25], v[164:167], v[200:203], v[22:25]
	v_mfma_f32_16x16x32_bf16 v[18:21], v[172:175], v[200:203], v[18:21]
	v_mfma_f32_16x16x32_bf16 v[6:9], v[164:167], v[208:211], v[6:9]
	v_mfma_f32_16x16x32_bf16 v[2:5], v[172:175], v[208:211], v[2:5]
	s_setprio 0
	s_mov_b32 s99, s58
	s_mov_b64 s[46:47], s[48:49]
	s_mov_b32 s50, s58
	s_add_i32 s58, s50, 2
	s_add_u32 s48, s46, 0x100
	s_addc_u32 s49, s47, 0
	s_add_u32 s1, s9, s46
	s_addc_u32 s51, s36, s47
	s_cmp_eq_u32 s56, s50
	s_cselect_b32 s50, 0, s48
	s_cselect_b32 s59, 0, s49
	s_cselect_b32 s60, s44, s1
	s_cselect_b32 s61, s45, s51
	s_add_u32 s50, s2, s50
	s_addc_u32 s51, s3, s59
	s_add_i32 s1, 0, 0x10000
	s_add_i32 s59, 0, 0x14000
	s_cmp_ge_i32 s99, s55
	s_barrier
	s_cbranch_scc0 .Lrot_z

; #define PG8_STAGE(bufoff, gbase, voff) do { _Pragma("unroll") for (int _i = 0; _i < 2; ++_i) \
;         __builtin_amdgcn_global_load_lds((const unsigned*)((const char*)(gbase) + (voff)[_i]), (LAS unsigned*)(lds + (bufoff) + ldsw + _i * 8192), 16, 0, 0); } while (0)
; #define PG8_LDA(dst, b, h) do { _Pragma("unroll") for (int m = 0; m < 4; ++m) _Pragma("unroll") for (int k = 0; k < 2; ++k) dst[m][k] = *(const LAS bf16x8*)(lds + PG8_SA(b, h) + aoff + m * 2048 + k * 1024); } while (0)
; #define PG8_LDB(dst, b, h) do { _Pragma("unroll") for (int n = 0; n < 2; ++n) _Pragma("unroll") for (int k = 0; k < 2; ++k) dst[n][k] = *(const LAS bf16x8*)(lds + PG8_SB(b, h) + boff + n * 2048 + k * 1024); } while (0)
; #define PG8_MMA(ai, bj, At, Bt) do { __builtin_amdgcn_s_setprio(1); _Pragma("unroll") for (int m = 0; m < 4; ++m) _Pragma("unroll") for (int n = 0; n < 2; ++n) _Pragma("unroll") for (int k = 0; k < 2; ++k) \
;         acc[ai][bj][m][n] = __builtin_amdgcn_mfma_f32_16x16x32_bf16(Bt[n][k], At[m][k], acc[ai][bj][m][n], 0, 0, 0); __builtin_amdgcn_s_setprio(0); } while (0)
; #define PG8_WAIT_V(n) asm volatile("s_waitcnt vmcnt(" #n ")" ::: "memory")
; #define PG8_WAIT_L(n) asm volatile("s_waitcnt lgkmcnt(" #n ")" ::: "memory")
; #define PG8_BAR __builtin_amdgcn_s_barrier()
; #define PG8_SCHED __builtin_amdgcn_sched_barrier(0)
; template <class Epi, class Sched>
; __device__ __forceinline__ void gemm_phase(LAS unsigned char* lds, const Gemm g, const Sched& S, const Epi& E) {
;     ...
;             PG8_LDB(B0, 0, 0); PG8_LDB(B1, 0, 1); PG8_SCHED; PG8_LDA(At, 0, 0); PG8_STAGE(PG8_SA(1, 1), a1 + hstep, voffA);
;             PG8_WAIT_V(8); PG8_WAIT_L(0); PG8_BAR; PG8_MMA(0, 0, At, B0); PG8_MMA(0, 1, At, B1); PG8_BAR; PG8_SCHED;
;             PG8_LDA(At, 0, 1); PG8_STAGE(PG8_SB(0, 0), b2, voffB); PG8_STAGE(PG8_SB(0, 1), b2 + hstep, voffB); PG8_STAGE(PG8_SA(0, 0), a2, voffA);
;             PG8_WAIT_V(8); PG8_WAIT_L(0); PG8_BAR; PG8_MMA(1, 0, At, B0); PG8_MMA(1, 1, At, B1); PG8_BAR; PG8_SCHED;
.Lrot_wout:
	v_add_u32_e32 v154, s1, v160
	v_add_u32_e32 v158, s59, v160
	ds_read_b128 v[130:133], v154
	ds_read_b128 v[134:137], v154 offset:1024
	ds_read_b128 v[138:141], v154 offset:2048
	ds_read_b128 v[154:157], v154 offset:3072
	ds_read_b128 v[162:165], v158
	ds_read_b128 v[166:169], v158 offset:1024
	ds_read_b128 v[170:173], v158 offset:2048
	ds_read_b128 v[174:177], v158 offset:3072
	s_add_u32 s48, s48, s2
	s_addc_u32 s49, s49, s3
	s_add_u32 s48, s48, s26
	s_addc_u32 s49, s49, s27
	s_add_u32 s48, s48, 0x80
	s_addc_u32 s49, s49, 0
	s_add_i32 m0, s5, 0xc000
	ds_read_b128 v[178:181], v161
	ds_read_b128 v[182:185], v161 offset:1024
	ds_read_b128 v[192:195], v161 offset:2048
	ds_read_b128 v[196:199], v161 offset:3072
	ds_read_b128 v[200:203], v161 offset:4096
	ds_read_b128 v[204:207], v161 offset:5120
	ds_read_b128 v[208:211], v161 offset:6144
	ds_read_b128 v[212:215], v161 offset:7168
	global_load_lds_dwordx4 v146, s[48:49]
	s_add_i32 m0, s5, 0xe000
	s_nop 0
	global_load_lds_dwordx4 v144, s[48:49]
	s_waitcnt vmcnt(8)
	s_waitcnt lgkmcnt(0)
	s_barrier
	s_setprio 1
	s_waitcnt lgkmcnt(0)
	v_mfma_f32_16x16x32_bf16 v[122:125], v[130:133], v[178:181], v[122:125]
	v_mfma_f32_16x16x32_bf16 v[126:129], v[138:141], v[178:181], v[126:129]
	v_mfma_f32_16x16x32_bf16 v[110:113], v[130:133], v[192:195], v[110:113]
	v_mfma_f32_16x16x32_bf16 v[106:109], v[138:141], v[192:195], v[106:109]
	v_mfma_f32_16x16x32_bf16 v[94:97], v[130:133], v[200:203], v[94:97]
	v_mfma_f32_16x16x32_bf16 v[90:93], v[138:141], v[200:203], v[90:93]
	v_mfma_f32_16x16x32_bf16 v[78:81], v[130:133], v[208:211], v[78:81]
	v_mfma_f32_16x16x32_bf16 v[74:77], v[138:141], v[208:211], v[74:77]
	v_mfma_f32_16x16x32_bf16 v[122:125], v[134:137], v[182:185], v[122:125]
	v_mfma_f32_16x16x32_bf16 v[126:129], v[154:157], v[182:185], v[126:129]
	v_mfma_f32_16x16x32_bf16 v[110:113], v[134:137], v[196:199], v[110:113]
	v_mfma_f32_16x16x32_bf16 v[106:109], v[154:157], v[196:199], v[106:109]
	v_mfma_f32_16x16x32_bf16 v[94:97], v[134:137], v[204:207], v[94:97]
	v_mfma_f32_16x16x32_bf16 v[90:93], v[154:157], v[204:207], v[90:93]
	v_mfma_f32_16x16x32_bf16 v[78:81], v[134:137], v[212:215], v[78:81]
	v_mfma_f32_16x16x32_bf16 v[74:77], v[154:157], v[212:215], v[74:77]
	s_setprio 0
	s_setprio 1
	v_mfma_f32_16x16x32_bf16 v[118:121], v[162:165], v[178:181], v[118:121]
	v_mfma_f32_16x16x32_bf16 v[114:117], v[170:173], v[178:181], v[114:117]
	v_mfma_f32_16x16x32_bf16 v[102:105], v[162:165], v[192:195], v[102:105]
	v_mfma_f32_16x16x32_bf16 v[98:101], v[170:173], v[192:195], v[98:101]
	v_mfma_f32_16x16x32_bf16 v[86:89], v[162:165], v[200:203], v[86:89]
	v_mfma_f32_16x16x32_bf16 v[82:85], v[170:173], v[200:203], v[82:85]
	v_mfma_f32_16x16x32_bf16 v[70:73], v[162:165], v[208:211], v[70:73]
	v_mfma_f32_16x16x32_bf16 v[66:69], v[170:173], v[208:211], v[66:69]
	v_mfma_f32_16x16x32_bf16 v[118:121], v[166:169], v[182:185], v[118:121]
	v_mfma_f32_16x16x32_bf16 v[114:117], v[174:177], v[182:185], v[114:117]
	v_mfma_f32_16x16x32_bf16 v[102:105], v[166:169], v[196:199], v[102:105]
	v_mfma_f32_16x16x32_bf16 v[98:101], v[174:177], v[196:199], v[98:101]
	v_mfma_f32_16x16x32_bf16 v[86:89], v[166:169], v[204:207], v[86:89]
	v_mfma_f32_16x16x32_bf16 v[82:85], v[174:177], v[204:207], v[82:85]
	v_mfma_f32_16x16x32_bf16 v[70:73], v[166:169], v[212:215], v[70:73]
	v_mfma_f32_16x16x32_bf16 v[66:69], v[174:177], v[212:215], v[66:69]
	s_setprio 0
	s_barrier
	s_add_i32 s1, s1, s4
	s_mov_b32 m0, s1
	ds_read_b128 v[178:181], v161 offset:16384
	ds_read_b128 v[182:185], v161 offset:17408
	ds_read_b128 v[192:195], v161 offset:18432
	ds_read_b128 v[196:199], v161 offset:19456
	ds_read_b128 v[200:203], v161 offset:20480
	ds_read_b128 v[204:207], v161 offset:21504
	ds_read_b128 v[208:211], v161 offset:22528
	ds_read_b128 v[212:215], v161 offset:23552
	global_load_lds_dwordx4 v0, s[60:61]
	s_add_i32 m0, s1, 0x2000
	s_add_u32 s48, s60, s26
	s_addc_u32 s49, s61, s27
	s_add_i32 s1, s59, s4
	global_load_lds_dwordx4 v142, s[60:61]
	s_mov_b32 m0, s1
	s_nop 0
	global_load_lds_dwordx4 v0, s[48:49]
	s_add_i32 m0, s1, 0x2000
	s_nop 0
	global_load_lds_dwordx4 v142, s[48:49]
	s_mov_b32 m0, s5
	s_nop 0
	global_load_lds_dwordx4 v146, s[52:53]
	s_mov_b32 m0, s18
	s_nop 0
	global_load_lds_dwordx4 v144, s[52:53]
	s_waitcnt vmcnt(8)
	s_waitcnt lgkmcnt(0)
	s_barrier
	s_setprio 1
	s_waitcnt lgkmcnt(0)
	v_mfma_f32_16x16x32_bf16 v[62:65], v[130:133], v[178:181], v[62:65]
	v_mfma_f32_16x16x32_bf16 v[58:61], v[138:141], v[178:181], v[58:61]
	v_mfma_f32_16x16x32_bf16 v[46:49], v[130:133], v[192:195], v[46:49]
	v_mfma_f32_16x16x32_bf16 v[42:45], v[138:141], v[192:195], v[42:45]
	v_mfma_f32_16x16x32_bf16 v[30:33], v[130:133], v[200:203], v[30:33]
	v_mfma_f32_16x16x32_bf16 v[26:29], v[138:141], v[200:203], v[26:29]
	v_mfma_f32_16x16x32_bf16 v[14:17], v[130:133], v[208:211], v[14:17]
	v_mfma_f32_16x16x32_bf16 v[10:13], v[138:141], v[208:211], v[10:13]
	v_mfma_f32_16x16x32_bf16 v[62:65], v[134:137], v[182:185], v[62:65]
	v_mfma_f32_16x16x32_bf16 v[58:61], v[154:157], v[182:185], v[58:61]
	v_mfma_f32_16x16x32_bf16 v[46:49], v[134:137], v[196:199], v[46:49]
	v_mfma_f32_16x16x32_bf16 v[42:45], v[154:157], v[196:199], v[42:45]
	v_mfma_f32_16x16x32_bf16 v[30:33], v[134:137], v[204:207], v[30:33]
	v_mfma_f32_16x16x32_bf16 v[26:29], v[154:157], v[204:207], v[26:29]
	v_mfma_f32_16x16x32_bf16 v[14:17], v[134:137], v[212:215], v[14:17]
	v_mfma_f32_16x16x32_bf16 v[10:13], v[154:157], v[212:215], v[10:13]
	s_setprio 0
	s_setprio 1
	v_mfma_f32_16x16x32_bf16 v[54:57], v[162:165], v[178:181], v[54:57]
	v_mfma_f32_16x16x32_bf16 v[50:53], v[170:173], v[178:181], v[50:53]
	v_mfma_f32_16x16x32_bf16 v[38:41], v[162:165], v[192:195], v[38:41]
	v_mfma_f32_16x16x32_bf16 v[34:37], v[170:173], v[192:195], v[34:37]
	v_mfma_f32_16x16x32_bf16 v[22:25], v[162:165], v[200:203], v[22:25]
	v_mfma_f32_16x16x32_bf16 v[18:21], v[170:173], v[200:203], v[18:21]
	v_mfma_f32_16x16x32_bf16 v[6:9], v[162:165], v[208:211], v[6:9]
	v_mfma_f32_16x16x32_bf16 v[2:5], v[170:173], v[208:211], v[2:5]
	v_mfma_f32_16x16x32_bf16 v[54:57], v[166:169], v[182:185], v[54:57]
	v_mfma_f32_16x16x32_bf16 v[50:53], v[174:177], v[182:185], v[50:53]
	v_mfma_f32_16x16x32_bf16 v[38:41], v[166:169], v[196:199], v[38:41]
	v_mfma_f32_16x16x32_bf16 v[34:37], v[174:177], v[196:199], v[34:37]
	v_mfma_f32_16x16x32_bf16 v[22:25], v[166:169], v[204:207], v[22:25]
	v_mfma_f32_16x16x32_bf16 v[18:21], v[174:177], v[204:207], v[18:21]
	v_mfma_f32_16x16x32_bf16 v[6:9], v[166:169], v[212:215], v[6:9]
	v_mfma_f32_16x16x32_bf16 v[2:5], v[174:177], v[212:215], v[2:5]
	s_setprio 0
	s_barrier
; #define PG8_STAGE(bufoff, gbase, voff) do { _Pragma("unroll") for (int _i = 0; _i < 2; ++_i) \
;         __builtin_amdgcn_global_load_lds((const unsigned*)((const char*)(gbase) + (voff)[_i]), (LAS unsigned*)(lds + (bufoff) + ldsw + _i * 8192), 16, 0, 0); } while (0)
; #define PG8_LDA(dst, b, h) do { _Pragma("unroll") for (int m = 0; m < 4; ++m) _Pragma("unroll") for (int k = 0; k < 2; ++k) dst[m][k] = *(const LAS bf16x8*)(lds + PG8_SA(b, h) + aoff + m * 2048 + k * 1024); } while (0)
; #define PG8_LDB(dst, b, h) do { _Pragma("unroll") for (int n = 0; n < 2; ++n) _Pragma("unroll") for (int k = 0; k < 2; ++k) dst[n][k] = *(const LAS bf16x8*)(lds + PG8_SB(b, h) + boff + n * 2048 + k * 1024); } while (0)
; #define PG8_MMA(ai, bj, At, Bt) do { __builtin_amdgcn_s_setprio(1); _Pragma("unroll") for (int m = 0; m < 4; ++m) _Pragma("unroll") for (int n = 0; n < 2; ++n) _Pragma("unroll") for (int k = 0; k < 2; ++k) \
;         acc[ai][bj][m][n] = __builtin_amdgcn_mfma_f32_16x16x32_bf16(Bt[n][k], At[m][k], acc[ai][bj][m][n], 0, 0, 0); __builtin_amdgcn_s_setprio(0); } while (0)
; #define PG8_WAIT_V(n) asm volatile("s_waitcnt vmcnt(" #n ")" ::: "memory")
; #define PG8_WAIT_L(n) asm volatile("s_waitcnt lgkmcnt(" #n ")" ::: "memory")
; #define PG8_BAR __builtin_amdgcn_s_barrier()
; #define PG8_SCHED __builtin_amdgcn_sched_barrier(0)
; template <class Epi, class Sched>
; __device__ __forceinline__ void gemm_phase(LAS unsigned char* lds, const Gemm g, const Sched& S, const Epi& E) {
;     ...
;             PG8_LDB(B0, 1, 0); PG8_LDB(B1, 1, 1); PG8_SCHED; PG8_LDA(At, 1, 0); PG8_STAGE(PG8_SA(0, 1), a2 + hstep, voffA);
;             PG8_WAIT_V(8); PG8_WAIT_L(0); PG8_BAR; PG8_MMA(0, 0, At, B0); PG8_MMA(0, 1, At, B1); PG8_BAR; PG8_SCHED;
	s_add_i32 s1, 0, 0x18000
	s_add_i32 s59, 0, 0x1c000
	v_add_u32_e32 v154, s1, v160
	v_add_u32_e32 v174, s59, v160
	ds_read_b128 v[130:133], v154
	ds_read_b128 v[134:137], v154 offset:1024
	ds_read_b128 v[138:141], v154 offset:2048
	ds_read_b128 v[154:157], v154 offset:3072
	ds_read_b128 v[162:165], v174
	ds_read_b128 v[166:169], v174 offset:1024
	ds_read_b128 v[170:173], v174 offset:2048
	ds_read_b128 v[174:177], v174 offset:3072
	s_add_u32 s48, s52, s26
	s_addc_u32 s49, s53, s27
	s_mov_b32 m0, s19
	ds_read_b128 v[178:181], v161 offset:32768
	ds_read_b128 v[182:185], v161 offset:33792
	ds_read_b128 v[192:195], v161 offset:34816
	ds_read_b128 v[196:199], v161 offset:35840
	ds_read_b128 v[200:203], v161 offset:36864
	ds_read_b128 v[204:207], v161 offset:37888
	ds_read_b128 v[208:211], v161 offset:38912
	ds_read_b128 v[212:215], v161 offset:39936
	global_load_lds_dwordx4 v146, s[48:49]
	s_mov_b32 m0, s20
	s_nop 0
	global_load_lds_dwordx4 v144, s[48:49]
	s_waitcnt vmcnt(8)
	s_waitcnt lgkmcnt(0)
	s_barrier
	s_setprio 1
	s_waitcnt lgkmcnt(0)
	v_mfma_f32_16x16x32_bf16 v[122:125], v[130:133], v[178:181], v[122:125]
	v_mfma_f32_16x16x32_bf16 v[126:129], v[138:141], v[178:181], v[126:129]
	v_mfma_f32_16x16x32_bf16 v[110:113], v[130:133], v[192:195], v[110:113]
	v_mfma_f32_16x16x32_bf16 v[106:109], v[138:141], v[192:195], v[106:109]
	v_mfma_f32_16x16x32_bf16 v[94:97], v[130:133], v[200:203], v[94:97]
	v_mfma_f32_16x16x32_bf16 v[90:93], v[138:141], v[200:203], v[90:93]
	v_mfma_f32_16x16x32_bf16 v[78:81], v[130:133], v[208:211], v[78:81]
	v_mfma_f32_16x16x32_bf16 v[74:77], v[138:141], v[208:211], v[74:77]
	v_mfma_f32_16x16x32_bf16 v[122:125], v[134:137], v[182:185], v[122:125]
	v_mfma_f32_16x16x32_bf16 v[126:129], v[154:157], v[182:185], v[126:129]
	v_mfma_f32_16x16x32_bf16 v[110:113], v[134:137], v[196:199], v[110:113]
	v_mfma_f32_16x16x32_bf16 v[106:109], v[154:157], v[196:199], v[106:109]
	v_mfma_f32_16x16x32_bf16 v[94:97], v[134:137], v[204:207], v[94:97]
	v_mfma_f32_16x16x32_bf16 v[90:93], v[154:157], v[204:207], v[90:93]
	v_mfma_f32_16x16x32_bf16 v[78:81], v[134:137], v[212:215], v[78:81]
	v_mfma_f32_16x16x32_bf16 v[74:77], v[154:157], v[212:215], v[74:77]
	s_setprio 0
	s_setprio 1
	v_mfma_f32_16x16x32_bf16 v[118:121], v[162:165], v[178:181], v[118:121]
	v_mfma_f32_16x16x32_bf16 v[114:117], v[170:173], v[178:181], v[114:117]
	v_mfma_f32_16x16x32_bf16 v[102:105], v[162:165], v[192:195], v[102:105]
	v_mfma_f32_16x16x32_bf16 v[98:101], v[170:173], v[192:195], v[98:101]
	v_mfma_f32_16x16x32_bf16 v[86:89], v[162:165], v[200:203], v[86:89]
	v_mfma_f32_16x16x32_bf16 v[82:85], v[170:173], v[200:203], v[82:85]
	v_mfma_f32_16x16x32_bf16 v[70:73], v[162:165], v[208:211], v[70:73]
	v_mfma_f32_16x16x32_bf16 v[66:69], v[170:173], v[208:211], v[66:69]
	v_mfma_f32_16x16x32_bf16 v[118:121], v[166:169], v[182:185], v[118:121]
	v_mfma_f32_16x16x32_bf16 v[114:117], v[174:177], v[182:185], v[114:117]
	v_mfma_f32_16x16x32_bf16 v[102:105], v[166:169], v[196:199], v[102:105]
	v_mfma_f32_16x16x32_bf16 v[98:101], v[174:177], v[196:199], v[98:101]
	v_mfma_f32_16x16x32_bf16 v[86:89], v[166:169], v[204:207], v[86:89]
	v_mfma_f32_16x16x32_bf16 v[82:85], v[174:177], v[204:207], v[82:85]
	v_mfma_f32_16x16x32_bf16 v[70:73], v[166:169], v[212:215], v[70:73]
	v_mfma_f32_16x16x32_bf16 v[66:69], v[174:177], v[212:215], v[66:69]
	s_setprio 0
	s_barrier
; #define PG8_STAGE(bufoff, gbase, voff) do { _Pragma("unroll") for (int _i = 0; _i < 2; ++_i) \
;         __builtin_amdgcn_global_load_lds((const unsigned*)((const char*)(gbase) + (voff)[_i]), (LAS unsigned*)(lds + (bufoff) + ldsw + _i * 8192), 16, 0, 0); } while (0)
; #define PG8_LDA(dst, b, h) do { _Pragma("unroll") for (int m = 0; m < 4; ++m) _Pragma("unroll") for (int k = 0; k < 2; ++k) dst[m][k] = *(const LAS bf16x8*)(lds + PG8_SA(b, h) + aoff + m * 2048 + k * 1024); } while (0)
; #define PG8_MMA(ai, bj, At, Bt) do { __builtin_amdgcn_s_setprio(1); _Pragma("unroll") for (int m = 0; m < 4; ++m) _Pragma("unroll") for (int n = 0; n < 2; ++n) _Pragma("unroll") for (int k = 0; k < 2; ++k) \
;         acc[ai][bj][m][n] = __builtin_amdgcn_mfma_f32_16x16x32_bf16(Bt[n][k], At[m][k], acc[ai][bj][m][n], 0, 0, 0); __builtin_amdgcn_s_setprio(0); } while (0)
; #define PG8_WAIT_V(n) asm volatile("s_waitcnt vmcnt(" #n ")" ::: "memory")
; #define PG8_WAIT_L(n) asm volatile("s_waitcnt lgkmcnt(" #n ")" ::: "memory")
; #define PG8_BAR __builtin_amdgcn_s_barrier()
; #define PG8_SCHED __builtin_amdgcn_sched_barrier(0)
; template <class Epi, class Sched>
; __device__ __forceinline__ void gemm_phase(LAS unsigned char* lds, const Gemm g, const Sched& S, const Epi& E) {
;     ...
;         for (int t = 0; t < nt; t += 2) {
;             const bool last = (t == nt - 2);
;             const char* a1 = cA + (size_t)(t + 1) * kstep;
;             const char* a2 = last ? nA : cA + (size_t)(t + 2) * kstep; const char* b2 = last ? nB : cB + (size_t)(t + 2) * kstep;
;             const char* a3 = a2 + kstep; const char* b3 = b2 + kstep;
;     ...
;             PG8_LDA(At, 1, 1); PG8_STAGE(PG8_SB(1, 0), b3, voffB); PG8_STAGE(PG8_SB(1, 1), b3 + hstep, voffB); PG8_STAGE(PG8_SA(1, 0), a3, voffA);
;             PG8_WAIT_V(8); PG8_WAIT_L(0); PG8_BAR; PG8_MMA(1, 0, At, B0); PG8_MMA(1, 1, At, B1); PG8_BAR; PG8_SCHED;
	s_add_i32 s1, s1, s4
	s_add_u32 s48, s60, 0x80
	s_addc_u32 s49, s61, 0
	s_mov_b32 m0, s1
	ds_read_b128 v[178:181], v161 offset:49152
	ds_read_b128 v[182:185], v161 offset:50176
	ds_read_b128 v[192:195], v161 offset:51200
	ds_read_b128 v[196:199], v161 offset:52224
	ds_read_b128 v[200:203], v161 offset:53248
	ds_read_b128 v[204:207], v161 offset:54272
	ds_read_b128 v[208:211], v161 offset:55296
	ds_read_b128 v[212:215], v161 offset:56320
	global_load_lds_dwordx4 v0, s[48:49]
	s_add_i32 m0, s1, 0x2000
	s_add_i32 s1, s59, s4
	global_load_lds_dwordx4 v142, s[48:49]
	s_add_u32 s48, s48, s26
	s_addc_u32 s49, s49, s27
	s_mov_b32 m0, s1
	s_nop 0
	global_load_lds_dwordx4 v0, s[48:49]
	s_add_i32 m0, s1, 0x2000
	s_nop 0
	global_load_lds_dwordx4 v142, s[48:49]
	s_add_u32 s48, s52, 0x80
	s_addc_u32 s49, s53, 0
	s_mov_b32 m0, s54
	s_nop 0
	global_load_lds_dwordx4 v146, s[48:49]
	s_mov_b32 m0, s55
	s_nop 0
	global_load_lds_dwordx4 v144, s[48:49]
	s_waitcnt vmcnt(8)
	s_waitcnt lgkmcnt(0)
	s_barrier
	s_setprio 1
	s_waitcnt lgkmcnt(0)
	v_mfma_f32_16x16x32_bf16 v[62:65], v[130:133], v[178:181], v[62:65]
	v_mfma_f32_16x16x32_bf16 v[58:61], v[138:141], v[178:181], v[58:61]
	v_mfma_f32_16x16x32_bf16 v[46:49], v[130:133], v[192:195], v[46:49]
	v_mfma_f32_16x16x32_bf16 v[42:45], v[138:141], v[192:195], v[42:45]
	v_mfma_f32_16x16x32_bf16 v[30:33], v[130:133], v[200:203], v[30:33]
	v_mfma_f32_16x16x32_bf16 v[26:29], v[138:141], v[200:203], v[26:29]
	v_mfma_f32_16x16x32_bf16 v[14:17], v[130:133], v[208:211], v[14:17]
	v_mfma_f32_16x16x32_bf16 v[10:13], v[138:141], v[208:211], v[10:13]
	v_mfma_f32_16x16x32_bf16 v[62:65], v[134:137], v[182:185], v[62:65]
	v_mfma_f32_16x16x32_bf16 v[58:61], v[154:157], v[182:185], v[58:61]
	v_mfma_f32_16x16x32_bf16 v[46:49], v[134:137], v[196:199], v[46:49]
	v_mfma_f32_16x16x32_bf16 v[42:45], v[154:157], v[196:199], v[42:45]
	v_mfma_f32_16x16x32_bf16 v[30:33], v[134:137], v[204:207], v[30:33]
	v_mfma_f32_16x16x32_bf16 v[26:29], v[154:157], v[204:207], v[26:29]
	v_mfma_f32_16x16x32_bf16 v[14:17], v[134:137], v[212:215], v[14:17]
	v_mfma_f32_16x16x32_bf16 v[10:13], v[154:157], v[212:215], v[10:13]
	s_setprio 0
	s_setprio 1
	v_mfma_f32_16x16x32_bf16 v[54:57], v[162:165], v[178:181], v[54:57]
	v_mfma_f32_16x16x32_bf16 v[50:53], v[170:173], v[178:181], v[50:53]
	v_mfma_f32_16x16x32_bf16 v[38:41], v[162:165], v[192:195], v[38:41]
	v_mfma_f32_16x16x32_bf16 v[34:37], v[170:173], v[192:195], v[34:37]
	v_mfma_f32_16x16x32_bf16 v[22:25], v[162:165], v[200:203], v[22:25]
	v_mfma_f32_16x16x32_bf16 v[18:21], v[170:173], v[200:203], v[18:21]
	v_mfma_f32_16x16x32_bf16 v[6:9], v[162:165], v[208:211], v[6:9]
	v_mfma_f32_16x16x32_bf16 v[2:5], v[170:173], v[208:211], v[2:5]
	v_mfma_f32_16x16x32_bf16 v[54:57], v[166:169], v[182:185], v[54:57]
	v_mfma_f32_16x16x32_bf16 v[50:53], v[174:177], v[182:185], v[50:53]
	v_mfma_f32_16x16x32_bf16 v[38:41], v[166:169], v[196:199], v[38:41]
	v_mfma_f32_16x16x32_bf16 v[34:37], v[174:177], v[196:199], v[34:37]
	v_mfma_f32_16x16x32_bf16 v[22:25], v[166:169], v[204:207], v[22:25]
	v_mfma_f32_16x16x32_bf16 v[18:21], v[174:177], v[204:207], v[18:21]
	v_mfma_f32_16x16x32_bf16 v[6:9], v[166:169], v[212:215], v[6:9]
	v_mfma_f32_16x16x32_bf16 v[2:5], v[174:177], v[212:215], v[2:5]
	s_setprio 0
	s_mov_b32 s99, s58
	s_mov_b64 s[48:49], s[50:51]
	s_mov_b32 s52, s58
	s_add_i32 s58, s52, 2
	s_add_u32 s50, s48, 0x100
	s_addc_u32 s51, s49, 0
	s_add_u32 s1, s9, s48
	s_addc_u32 s53, s36, s49
	s_cmp_eq_u32 s56, s52
	s_cselect_b32 s52, 0, s50
	s_cselect_b32 s59, 0, s51
	s_cselect_b32 s60, s46, s1
	s_cselect_b32 s61, s47, s53
	s_add_u32 s52, s2, s52
	s_addc_u32 s53, s3, s59
	s_add_i32 s1, 0, 0x10000
	s_add_i32 s59, 0, 0x14000
	s_cmp_ge_i32 s99, s21
	s_barrier
	s_cbranch_scc0 .Lrot_wout

; #define PG8_STAGE(bufoff, gbase, voff) do { _Pragma("unroll") for (int _i = 0; _i < 2; ++_i) \
;         __builtin_amdgcn_global_load_lds((const unsigned*)((const char*)(gbase) + (voff)[_i]), (LAS unsigned*)(lds + (bufoff) + ldsw + _i * 8192), 16, 0, 0); } while (0)
; #define PG8_LDA(dst, b, h) do { _Pragma("unroll") for (int m = 0; m < 4; ++m) _Pragma("unroll") for (int k = 0; k < 2; ++k) dst[m][k] = *(const LAS bf16x8*)(lds + PG8_SA(b, h) + aoff + m * 2048 + k * 1024); } while (0)
; #define PG8_LDB(dst, b, h) do { _Pragma("unroll") for (int n = 0; n < 2; ++n) _Pragma("unroll") for (int k = 0; k < 2; ++k) dst[n][k] = *(const LAS bf16x8*)(lds + PG8_SB(b, h) + boff + n * 2048 + k * 1024); } while (0)
; #define PG8_MMA(ai, bj, At, Bt) do { __builtin_amdgcn_s_setprio(1); _Pragma("unroll") for (int m = 0; m < 4; ++m) _Pragma("unroll") for (int n = 0; n < 2; ++n) _Pragma("unroll") for (int k = 0; k < 2; ++k) \
;         acc[ai][bj][m][n] = __builtin_amdgcn_mfma_f32_16x16x32_bf16(Bt[n][k], At[m][k], acc[ai][bj][m][n], 0, 0, 0); __builtin_amdgcn_s_setprio(0); } while (0)
; #define PG8_WAIT_V(n) asm volatile("s_waitcnt vmcnt(" #n ")" ::: "memory")
; #define PG8_WAIT_L(n) asm volatile("s_waitcnt lgkmcnt(" #n ")" ::: "memory")
; #define PG8_BAR __builtin_amdgcn_s_barrier()
; #define PG8_SCHED __builtin_amdgcn_sched_barrier(0)
; template <class Epi, class Sched>
; __device__ __forceinline__ void gemm_phase(LAS unsigned char* lds, const Gemm g, const Sched& S, const Epi& E) {
;     ...
;             PG8_LDB(B0, 0, 0); PG8_LDB(B1, 0, 1); PG8_SCHED; PG8_LDA(At, 0, 0); PG8_STAGE(PG8_SA(1, 1), a1 + hstep, voffA);
;             PG8_WAIT_V(8); PG8_WAIT_L(0); PG8_BAR; PG8_MMA(0, 0, At, B0); PG8_MMA(0, 1, At, B1); PG8_BAR; PG8_SCHED;
;             PG8_LDA(At, 0, 1); PG8_STAGE(PG8_SB(0, 0), b2, voffB); PG8_STAGE(PG8_SB(0, 1), b2 + hstep, voffB); PG8_STAGE(PG8_SA(0, 0), a2, voffA);
;             PG8_WAIT_V(8); PG8_WAIT_L(0); PG8_BAR; PG8_MMA(1, 0, At, B0); PG8_MMA(1, 1, At, B1); PG8_BAR; PG8_SCHED;
.Lrot_mlp1:
	v_add_u32_e32 v156, s1, v142
	v_add_u32_e32 v172, s63, v142
	ds_read_b128 v[144:147], v156
	ds_read_b128 v[148:151], v156 offset:1024
	ds_read_b128 v[152:155], v156 offset:2048
	ds_read_b128 v[156:159], v156 offset:3072
	ds_read_b128 v[160:163], v172
	ds_read_b128 v[164:167], v172 offset:1024
	ds_read_b128 v[168:171], v172 offset:2048
	ds_read_b128 v[172:175], v172 offset:3072
	s_add_u32 s48, s48, s2
	s_addc_u32 s49, s49, s3
	s_add_u32 s48, s48, s26
	s_addc_u32 s49, s49, s27
	s_add_u32 s48, s48, 0x80
	s_addc_u32 s49, s49, 0
	s_add_i32 m0, s5, 0xc000
	ds_read_b128 v[176:179], v143
	ds_read_b128 v[180:183], v143 offset:1024
	ds_read_b128 v[184:187], v143 offset:2048
	ds_read_b128 v[192:195], v143 offset:3072
	ds_read_b128 v[196:199], v143 offset:4096
	ds_read_b128 v[200:203], v143 offset:5120
	ds_read_b128 v[204:207], v143 offset:6144
	ds_read_b128 v[208:211], v143 offset:7168
	global_load_lds_dwordx4 v134, s[48:49]
	s_add_i32 m0, s5, 0xe000
	s_nop 0
	global_load_lds_dwordx4 v132, s[48:49]
	s_waitcnt vmcnt(8)
	s_waitcnt lgkmcnt(0)
	s_barrier
	s_setprio 1
	s_waitcnt lgkmcnt(0)
	v_mfma_f32_16x16x32_bf16 v[122:125], v[144:147], v[176:179], v[122:125]
	v_mfma_f32_16x16x32_bf16 v[126:129], v[152:155], v[176:179], v[126:129]
	v_mfma_f32_16x16x32_bf16 v[110:113], v[144:147], v[184:187], v[110:113]
	v_mfma_f32_16x16x32_bf16 v[106:109], v[152:155], v[184:187], v[106:109]
	v_mfma_f32_16x16x32_bf16 v[94:97], v[144:147], v[196:199], v[94:97]
	v_mfma_f32_16x16x32_bf16 v[90:93], v[152:155], v[196:199], v[90:93]
	v_mfma_f32_16x16x32_bf16 v[78:81], v[144:147], v[204:207], v[78:81]
	v_mfma_f32_16x16x32_bf16 v[74:77], v[152:155], v[204:207], v[74:77]
	v_mfma_f32_16x16x32_bf16 v[122:125], v[148:151], v[180:183], v[122:125]
	v_mfma_f32_16x16x32_bf16 v[126:129], v[156:159], v[180:183], v[126:129]
	v_mfma_f32_16x16x32_bf16 v[110:113], v[148:151], v[192:195], v[110:113]
	v_mfma_f32_16x16x32_bf16 v[106:109], v[156:159], v[192:195], v[106:109]
	v_mfma_f32_16x16x32_bf16 v[94:97], v[148:151], v[200:203], v[94:97]
	v_mfma_f32_16x16x32_bf16 v[90:93], v[156:159], v[200:203], v[90:93]
	v_mfma_f32_16x16x32_bf16 v[78:81], v[148:151], v[208:211], v[78:81]
	v_mfma_f32_16x16x32_bf16 v[74:77], v[156:159], v[208:211], v[74:77]
	s_setprio 0
	s_setprio 1
	v_mfma_f32_16x16x32_bf16 v[118:121], v[160:163], v[176:179], v[118:121]
	v_mfma_f32_16x16x32_bf16 v[114:117], v[168:171], v[176:179], v[114:117]
	v_mfma_f32_16x16x32_bf16 v[102:105], v[160:163], v[184:187], v[102:105]
	v_mfma_f32_16x16x32_bf16 v[98:101], v[168:171], v[184:187], v[98:101]
	v_mfma_f32_16x16x32_bf16 v[86:89], v[160:163], v[196:199], v[86:89]
	v_mfma_f32_16x16x32_bf16 v[82:85], v[168:171], v[196:199], v[82:85]
	v_mfma_f32_16x16x32_bf16 v[70:73], v[160:163], v[204:207], v[70:73]
	v_mfma_f32_16x16x32_bf16 v[66:69], v[168:171], v[204:207], v[66:69]
	v_mfma_f32_16x16x32_bf16 v[118:121], v[164:167], v[180:183], v[118:121]
	v_mfma_f32_16x16x32_bf16 v[114:117], v[172:175], v[180:183], v[114:117]
	v_mfma_f32_16x16x32_bf16 v[102:105], v[164:167], v[192:195], v[102:105]
	v_mfma_f32_16x16x32_bf16 v[98:101], v[172:175], v[192:195], v[98:101]
	v_mfma_f32_16x16x32_bf16 v[86:89], v[164:167], v[200:203], v[86:89]
	v_mfma_f32_16x16x32_bf16 v[82:85], v[172:175], v[200:203], v[82:85]
	v_mfma_f32_16x16x32_bf16 v[70:73], v[164:167], v[208:211], v[70:73]
	v_mfma_f32_16x16x32_bf16 v[66:69], v[172:175], v[208:211], v[66:69]
	s_setprio 0
	s_barrier
	s_add_i32 s1, s1, s4
	s_mov_b32 m0, s1
	ds_read_b128 v[176:179], v143 offset:16384
	ds_read_b128 v[180:183], v143 offset:17408
	ds_read_b128 v[184:187], v143 offset:18432
	ds_read_b128 v[192:195], v143 offset:19456
	ds_read_b128 v[196:199], v143 offset:20480
	ds_read_b128 v[200:203], v143 offset:21504
	ds_read_b128 v[204:207], v143 offset:22528
	ds_read_b128 v[208:211], v143 offset:23552
	global_load_lds_dwordx4 v0, s[64:65]
	s_add_i32 m0, s1, 0x2000
	s_add_u32 s48, s64, s26
	s_addc_u32 s49, s65, s27
	s_add_i32 s1, s63, s4
	global_load_lds_dwordx4 v130, s[64:65]
	s_mov_b32 m0, s1
	s_nop 0
	global_load_lds_dwordx4 v0, s[48:49]
	s_add_i32 m0, s1, 0x2000
	s_nop 0
	global_load_lds_dwordx4 v130, s[48:49]
	s_mov_b32 m0, s5
	s_nop 0
	global_load_lds_dwordx4 v134, s[52:53]
	s_mov_b32 m0, s54
	s_nop 0
	global_load_lds_dwordx4 v132, s[52:53]
	s_waitcnt vmcnt(8)
	s_waitcnt lgkmcnt(0)
	s_barrier
	s_setprio 1
	s_waitcnt lgkmcnt(0)
	v_mfma_f32_16x16x32_bf16 v[62:65], v[144:147], v[176:179], v[62:65]
	v_mfma_f32_16x16x32_bf16 v[58:61], v[152:155], v[176:179], v[58:61]
	v_mfma_f32_16x16x32_bf16 v[46:49], v[144:147], v[184:187], v[46:49]
	v_mfma_f32_16x16x32_bf16 v[42:45], v[152:155], v[184:187], v[42:45]
	v_mfma_f32_16x16x32_bf16 v[30:33], v[144:147], v[196:199], v[30:33]
	v_mfma_f32_16x16x32_bf16 v[26:29], v[152:155], v[196:199], v[26:29]
	v_mfma_f32_16x16x32_bf16 v[14:17], v[144:147], v[204:207], v[14:17]
	v_mfma_f32_16x16x32_bf16 v[10:13], v[152:155], v[204:207], v[10:13]
	v_mfma_f32_16x16x32_bf16 v[62:65], v[148:151], v[180:183], v[62:65]
	v_mfma_f32_16x16x32_bf16 v[58:61], v[156:159], v[180:183], v[58:61]
	v_mfma_f32_16x16x32_bf16 v[46:49], v[148:151], v[192:195], v[46:49]
	v_mfma_f32_16x16x32_bf16 v[42:45], v[156:159], v[192:195], v[42:45]
	v_mfma_f32_16x16x32_bf16 v[30:33], v[148:151], v[200:203], v[30:33]
	v_mfma_f32_16x16x32_bf16 v[26:29], v[156:159], v[200:203], v[26:29]
	v_mfma_f32_16x16x32_bf16 v[14:17], v[148:151], v[208:211], v[14:17]
	v_mfma_f32_16x16x32_bf16 v[10:13], v[156:159], v[208:211], v[10:13]
	s_setprio 0
	s_setprio 1
	v_mfma_f32_16x16x32_bf16 v[54:57], v[160:163], v[176:179], v[54:57]
	v_mfma_f32_16x16x32_bf16 v[50:53], v[168:171], v[176:179], v[50:53]
	v_mfma_f32_16x16x32_bf16 v[38:41], v[160:163], v[184:187], v[38:41]
	v_mfma_f32_16x16x32_bf16 v[34:37], v[168:171], v[184:187], v[34:37]
	v_mfma_f32_16x16x32_bf16 v[22:25], v[160:163], v[196:199], v[22:25]
	v_mfma_f32_16x16x32_bf16 v[18:21], v[168:171], v[196:199], v[18:21]
	v_mfma_f32_16x16x32_bf16 v[6:9], v[160:163], v[204:207], v[6:9]
	v_mfma_f32_16x16x32_bf16 v[2:5], v[168:171], v[204:207], v[2:5]
	v_mfma_f32_16x16x32_bf16 v[54:57], v[164:167], v[180:183], v[54:57]
	v_mfma_f32_16x16x32_bf16 v[50:53], v[172:175], v[180:183], v[50:53]
	v_mfma_f32_16x16x32_bf16 v[38:41], v[164:167], v[192:195], v[38:41]
	v_mfma_f32_16x16x32_bf16 v[34:37], v[172:175], v[192:195], v[34:37]
	v_mfma_f32_16x16x32_bf16 v[22:25], v[164:167], v[200:203], v[22:25]
	v_mfma_f32_16x16x32_bf16 v[18:21], v[172:175], v[200:203], v[18:21]
	v_mfma_f32_16x16x32_bf16 v[6:9], v[164:167], v[208:211], v[6:9]
	v_mfma_f32_16x16x32_bf16 v[2:5], v[172:175], v[208:211], v[2:5]
	s_setprio 0
	s_barrier
; #define PG8_STAGE(bufoff, gbase, voff) do { _Pragma("unroll") for (int _i = 0; _i < 2; ++_i) \
;         __builtin_amdgcn_global_load_lds((const unsigned*)((const char*)(gbase) + (voff)[_i]), (LAS unsigned*)(lds + (bufoff) + ldsw + _i * 8192), 16, 0, 0); } while (0)
; #define PG8_LDA(dst, b, h) do { _Pragma("unroll") for (int m = 0; m < 4; ++m) _Pragma("unroll") for (int k = 0; k < 2; ++k) dst[m][k] = *(const LAS bf16x8*)(lds + PG8_SA(b, h) + aoff + m * 2048 + k * 1024); } while (0)
; #define PG8_LDB(dst, b, h) do { _Pragma("unroll") for (int n = 0; n < 2; ++n) _Pragma("unroll") for (int k = 0; k < 2; ++k) dst[n][k] = *(const LAS bf16x8*)(lds + PG8_SB(b, h) + boff + n * 2048 + k * 1024); } while (0)
; #define PG8_MMA(ai, bj, At, Bt) do { __builtin_amdgcn_s_setprio(1); _Pragma("unroll") for (int m = 0; m < 4; ++m) _Pragma("unroll") for (int n = 0; n < 2; ++n) _Pragma("unroll") for (int k = 0; k < 2; ++k) \
;         acc[ai][bj][m][n] = __builtin_amdgcn_mfma_f32_16x16x32_bf16(Bt[n][k], At[m][k], acc[ai][bj][m][n], 0, 0, 0); __builtin_amdgcn_s_setprio(0); } while (0)
; #define PG8_WAIT_V(n) asm volatile("s_waitcnt vmcnt(" #n ")" ::: "memory")
; #define PG8_WAIT_L(n) asm volatile("s_waitcnt lgkmcnt(" #n ")" ::: "memory")
; #define PG8_BAR __builtin_amdgcn_s_barrier()
; #define PG8_SCHED __builtin_amdgcn_sched_barrier(0)
; template <class Epi, class Sched>
; __device__ __forceinline__ void gemm_phase(LAS unsigned char* lds, const Gemm g, const Sched& S, const Epi& E) {
;     ...
;             PG8_LDB(B0, 1, 0); PG8_LDB(B1, 1, 1); PG8_SCHED; PG8_LDA(At, 1, 0); PG8_STAGE(PG8_SA(0, 1), a2 + hstep, voffA);
;             PG8_WAIT_V(8); PG8_WAIT_L(0); PG8_BAR; PG8_MMA(0, 0, At, B0); PG8_MMA(0, 1, At, B1); PG8_BAR; PG8_SCHED;
	s_add_i32 s1, 0, 0x18000
	s_add_i32 s63, 0, 0x1c000
	v_add_u32_e32 v156, s1, v142
	v_add_u32_e32 v172, s63, v142
	ds_read_b128 v[144:147], v156
	ds_read_b128 v[148:151], v156 offset:1024
	ds_read_b128 v[152:155], v156 offset:2048
	ds_read_b128 v[156:159], v156 offset:3072
	ds_read_b128 v[160:163], v172
	ds_read_b128 v[164:167], v172 offset:1024
	ds_read_b128 v[168:171], v172 offset:2048
	ds_read_b128 v[172:175], v172 offset:3072
	s_add_u32 s48, s52, s26
	s_addc_u32 s49, s53, s27
	s_mov_b32 m0, s55
	ds_read_b128 v[176:179], v143 offset:32768
	ds_read_b128 v[180:183], v143 offset:33792
	ds_read_b128 v[184:187], v143 offset:34816
	ds_read_b128 v[192:195], v143 offset:35840
	ds_read_b128 v[196:199], v143 offset:36864
	ds_read_b128 v[200:203], v143 offset:37888
	ds_read_b128 v[204:207], v143 offset:38912
	ds_read_b128 v[208:211], v143 offset:39936
	global_load_lds_dwordx4 v134, s[48:49]
	s_mov_b32 m0, s56
	s_nop 0
	global_load_lds_dwordx4 v132, s[48:49]
	s_waitcnt vmcnt(8)
	s_waitcnt lgkmcnt(0)
	s_barrier
	s_setprio 1
	s_waitcnt lgkmcnt(0)
	v_mfma_f32_16x16x32_bf16 v[122:125], v[144:147], v[176:179], v[122:125]
	v_mfma_f32_16x16x32_bf16 v[126:129], v[152:155], v[176:179], v[126:129]
	v_mfma_f32_16x16x32_bf16 v[110:113], v[144:147], v[184:187], v[110:113]
	v_mfma_f32_16x16x32_bf16 v[106:109], v[152:155], v[184:187], v[106:109]
	v_mfma_f32_16x16x32_bf16 v[94:97], v[144:147], v[196:199], v[94:97]
	v_mfma_f32_16x16x32_bf16 v[90:93], v[152:155], v[196:199], v[90:93]
	v_mfma_f32_16x16x32_bf16 v[78:81], v[144:147], v[204:207], v[78:81]
	v_mfma_f32_16x16x32_bf16 v[74:77], v[152:155], v[204:207], v[74:77]
	v_mfma_f32_16x16x32_bf16 v[122:125], v[148:151], v[180:183], v[122:125]
	v_mfma_f32_16x16x32_bf16 v[126:129], v[156:159], v[180:183], v[126:129]
	v_mfma_f32_16x16x32_bf16 v[110:113], v[148:151], v[192:195], v[110:113]
	v_mfma_f32_16x16x32_bf16 v[106:109], v[156:159], v[192:195], v[106:109]
	v_mfma_f32_16x16x32_bf16 v[94:97], v[148:151], v[200:203], v[94:97]
	v_mfma_f32_16x16x32_bf16 v[90:93], v[156:159], v[200:203], v[90:93]
	v_mfma_f32_16x16x32_bf16 v[78:81], v[148:151], v[208:211], v[78:81]
	v_mfma_f32_16x16x32_bf16 v[74:77], v[156:159], v[208:211], v[74:77]
	s_setprio 0
	s_setprio 1
	v_mfma_f32_16x16x32_bf16 v[118:121], v[160:163], v[176:179], v[118:121]
	v_mfma_f32_16x16x32_bf16 v[114:117], v[168:171], v[176:179], v[114:117]
	v_mfma_f32_16x16x32_bf16 v[102:105], v[160:163], v[184:187], v[102:105]
	v_mfma_f32_16x16x32_bf16 v[98:101], v[168:171], v[184:187], v[98:101]
	v_mfma_f32_16x16x32_bf16 v[86:89], v[160:163], v[196:199], v[86:89]
	v_mfma_f32_16x16x32_bf16 v[82:85], v[168:171], v[196:199], v[82:85]
	v_mfma_f32_16x16x32_bf16 v[70:73], v[160:163], v[204:207], v[70:73]
	v_mfma_f32_16x16x32_bf16 v[66:69], v[168:171], v[204:207], v[66:69]
	v_mfma_f32_16x16x32_bf16 v[118:121], v[164:167], v[180:183], v[118:121]
	v_mfma_f32_16x16x32_bf16 v[114:117], v[172:175], v[180:183], v[114:117]
	v_mfma_f32_16x16x32_bf16 v[102:105], v[164:167], v[192:195], v[102:105]
	v_mfma_f32_16x16x32_bf16 v[98:101], v[172:175], v[192:195], v[98:101]
	v_mfma_f32_16x16x32_bf16 v[86:89], v[164:167], v[200:203], v[86:89]
	v_mfma_f32_16x16x32_bf16 v[82:85], v[172:175], v[200:203], v[82:85]
	v_mfma_f32_16x16x32_bf16 v[70:73], v[164:167], v[208:211], v[70:73]
	v_mfma_f32_16x16x32_bf16 v[66:69], v[172:175], v[208:211], v[66:69]
	s_setprio 0
	s_barrier
; #define PG8_STAGE(bufoff, gbase, voff) do { _Pragma("unroll") for (int _i = 0; _i < 2; ++_i) \
;         __builtin_amdgcn_global_load_lds((const unsigned*)((const char*)(gbase) + (voff)[_i]), (LAS unsigned*)(lds + (bufoff) + ldsw + _i * 8192), 16, 0, 0); } while (0)
; #define PG8_LDA(dst, b, h) do { _Pragma("unroll") for (int m = 0; m < 4; ++m) _Pragma("unroll") for (int k = 0; k < 2; ++k) dst[m][k] = *(const LAS bf16x8*)(lds + PG8_SA(b, h) + aoff + m * 2048 + k * 1024); } while (0)
; #define PG8_MMA(ai, bj, At, Bt) do { __builtin_amdgcn_s_setprio(1); _Pragma("unroll") for (int m = 0; m < 4; ++m) _Pragma("unroll") for (int n = 0; n < 2; ++n) _Pragma("unroll") for (int k = 0; k < 2; ++k) \
;         acc[ai][bj][m][n] = __builtin_amdgcn_mfma_f32_16x16x32_bf16(Bt[n][k], At[m][k], acc[ai][bj][m][n], 0, 0, 0); __builtin_amdgcn_s_setprio(0); } while (0)
; #define PG8_WAIT_V(n) asm volatile("s_waitcnt vmcnt(" #n ")" ::: "memory")
; #define PG8_WAIT_L(n) asm volatile("s_waitcnt lgkmcnt(" #n ")" ::: "memory")
; #define PG8_BAR __builtin_amdgcn_s_barrier()
; #define PG8_SCHED __builtin_amdgcn_sched_barrier(0)
; template <class Epi, class Sched>
; __device__ __forceinline__ void gemm_phase(LAS unsigned char* lds, const Gemm g, const Sched& S, const Epi& E) {
;     ...
;         for (int t = 0; t < nt; t += 2) {
;             const bool last = (t == nt - 2);
;             const char* a1 = cA + (size_t)(t + 1) * kstep;
;             const char* a2 = last ? nA : cA + (size_t)(t + 2) * kstep; const char* b2 = last ? nB : cB + (size_t)(t + 2) * kstep;
;             const char* a3 = a2 + kstep; const char* b3 = b2 + kstep;
;     ...
;             PG8_LDA(At, 1, 1); PG8_STAGE(PG8_SB(1, 0), b3, voffB); PG8_STAGE(PG8_SB(1, 1), b3 + hstep, voffB); PG8_STAGE(PG8_SA(1, 0), a3, voffA);
;             PG8_WAIT_V(8); PG8_WAIT_L(0); PG8_BAR; PG8_MMA(1, 0, At, B0); PG8_MMA(1, 1, At, B1); PG8_BAR; PG8_SCHED;
	s_add_i32 s1, s1, s4
	s_add_u32 s48, s64, 0x80
	s_addc_u32 s49, s65, 0
	s_mov_b32 m0, s1
	ds_read_b128 v[176:179], v143 offset:49152
	ds_read_b128 v[180:183], v143 offset:50176
	ds_read_b128 v[184:187], v143 offset:51200
	ds_read_b128 v[192:195], v143 offset:52224
	ds_read_b128 v[196:199], v143 offset:53248
	ds_read_b128 v[200:203], v143 offset:54272
	ds_read_b128 v[204:207], v143 offset:55296
	ds_read_b128 v[208:211], v143 offset:56320
	global_load_lds_dwordx4 v0, s[48:49]
	s_add_i32 m0, s1, 0x2000
	s_add_i32 s1, s63, s4
	global_load_lds_dwordx4 v130, s[48:49]
	s_add_u32 s48, s48, s26
	s_addc_u32 s49, s49, s27
	s_mov_b32 m0, s1
	s_nop 0
	global_load_lds_dwordx4 v0, s[48:49]
	s_add_i32 m0, s1, 0x2000
	s_nop 0
	global_load_lds_dwordx4 v130, s[48:49]
	s_add_u32 s48, s52, 0x80
	s_addc_u32 s49, s53, 0
	s_mov_b32 m0, s57
	s_nop 0
	global_load_lds_dwordx4 v134, s[48:49]
	s_mov_b32 m0, s58
	s_nop 0
	global_load_lds_dwordx4 v132, s[48:49]
	s_waitcnt vmcnt(8)
	s_waitcnt lgkmcnt(0)
	s_barrier
	s_setprio 1
	s_waitcnt lgkmcnt(0)
	v_mfma_f32_16x16x32_bf16 v[62:65], v[144:147], v[176:179], v[62:65]
	v_mfma_f32_16x16x32_bf16 v[58:61], v[152:155], v[176:179], v[58:61]
	v_mfma_f32_16x16x32_bf16 v[46:49], v[144:147], v[184:187], v[46:49]
	v_mfma_f32_16x16x32_bf16 v[42:45], v[152:155], v[184:187], v[42:45]
	v_mfma_f32_16x16x32_bf16 v[30:33], v[144:147], v[196:199], v[30:33]
	v_mfma_f32_16x16x32_bf16 v[26:29], v[152:155], v[196:199], v[26:29]
	v_mfma_f32_16x16x32_bf16 v[14:17], v[144:147], v[204:207], v[14:17]
	v_mfma_f32_16x16x32_bf16 v[10:13], v[152:155], v[204:207], v[10:13]
	v_mfma_f32_16x16x32_bf16 v[62:65], v[148:151], v[180:183], v[62:65]
	v_mfma_f32_16x16x32_bf16 v[58:61], v[156:159], v[180:183], v[58:61]
	v_mfma_f32_16x16x32_bf16 v[46:49], v[148:151], v[192:195], v[46:49]
	v_mfma_f32_16x16x32_bf16 v[42:45], v[156:159], v[192:195], v[42:45]
	v_mfma_f32_16x16x32_bf16 v[30:33], v[148:151], v[200:203], v[30:33]
	v_mfma_f32_16x16x32_bf16 v[26:29], v[156:159], v[200:203], v[26:29]
	v_mfma_f32_16x16x32_bf16 v[14:17], v[148:151], v[208:211], v[14:17]
	v_mfma_f32_16x16x32_bf16 v[10:13], v[156:159], v[208:211], v[10:13]
	s_setprio 0
	s_setprio 1
	v_mfma_f32_16x16x32_bf16 v[54:57], v[160:163], v[176:179], v[54:57]
	v_mfma_f32_16x16x32_bf16 v[50:53], v[168:171], v[176:179], v[50:53]
	v_mfma_f32_16x16x32_bf16 v[38:41], v[160:163], v[184:187], v[38:41]
	v_mfma_f32_16x16x32_bf16 v[34:37], v[168:171], v[184:187], v[34:37]
	v_mfma_f32_16x16x32_bf16 v[22:25], v[160:163], v[196:199], v[22:25]
	v_mfma_f32_16x16x32_bf16 v[18:21], v[168:171], v[196:199], v[18:21]
	v_mfma_f32_16x16x32_bf16 v[6:9], v[160:163], v[204:207], v[6:9]
	v_mfma_f32_16x16x32_bf16 v[2:5], v[168:171], v[204:207], v[2:5]
	v_mfma_f32_16x16x32_bf16 v[54:57], v[164:167], v[180:183], v[54:57]
	v_mfma_f32_16x16x32_bf16 v[50:53], v[172:175], v[180:183], v[50:53]
	v_mfma_f32_16x16x32_bf16 v[38:41], v[164:167], v[192:195], v[38:41]
	v_mfma_f32_16x16x32_bf16 v[34:37], v[172:175], v[192:195], v[34:37]
	v_mfma_f32_16x16x32_bf16 v[22:25], v[164:167], v[200:203], v[22:25]
	v_mfma_f32_16x16x32_bf16 v[18:21], v[172:175], v[200:203], v[18:21]
	v_mfma_f32_16x16x32_bf16 v[6:9], v[164:167], v[208:211], v[6:9]
	v_mfma_f32_16x16x32_bf16 v[2:5], v[172:175], v[208:211], v[2:5]
	s_setprio 0
	s_mov_b32 s99, s62
	s_mov_b64 s[48:49], s[50:51]
	s_mov_b32 s52, s62
	s_add_i32 s62, s52, 2
	s_add_u32 s50, s48, 0x100
	s_addc_u32 s51, s49, 0
	s_add_u32 s1, s9, s48
	s_addc_u32 s53, s36, s49
	s_cmp_eq_u32 s60, s52
	s_cselect_b32 s52, s100, s50
	s_cselect_b32 s63, 0, s51
	s_cselect_b32 s64, s46, s1
	s_cselect_b32 s65, s47, s53
	s_add_u32 s52, s2, s52
	s_addc_u32 s53, s3, s63
	s_add_i32 s1, 0, 0x10000
	s_add_i32 s63, 0, 0x14000
	s_cmp_ge_i32 s99, s59
	s_barrier
	s_cbranch_scc0 .Lrot_mlp1

; #define PG8_STAGE(bufoff, gbase, voff) do { _Pragma("unroll") for (int _i = 0; _i < 2; ++_i) \
;         __builtin_amdgcn_global_load_lds((const unsigned*)((const char*)(gbase) + (voff)[_i]), (LAS unsigned*)(lds + (bufoff) + ldsw + _i * 8192), 16, 0, 0); } while (0)
; #define PG8_LDA(dst, b, h) do { _Pragma("unroll") for (int m = 0; m < 4; ++m) _Pragma("unroll") for (int k = 0; k < 2; ++k) dst[m][k] = *(const LAS bf16x8*)(lds + PG8_SA(b, h) + aoff + m * 2048 + k * 1024); } while (0)
; #define PG8_LDB(dst, b, h) do { _Pragma("unroll") for (int n = 0; n < 2; ++n) _Pragma("unroll") for (int k = 0; k < 2; ++k) dst[n][k] = *(const LAS bf16x8*)(lds + PG8_SB(b, h) + boff + n * 2048 + k * 1024); } while (0)
; #define PG8_MMA(ai, bj, At, Bt) do { __builtin_amdgcn_s_setprio(1); _Pragma("unroll") for (int m = 0; m < 4; ++m) _Pragma("unroll") for (int n = 0; n < 2; ++n) _Pragma("unroll") for (int k = 0; k < 2; ++k) \
;         acc[ai][bj][m][n] = __builtin_amdgcn_mfma_f32_16x16x32_bf16(Bt[n][k], At[m][k], acc[ai][bj][m][n], 0, 0, 0); __builtin_amdgcn_s_setprio(0); } while (0)
; #define PG8_WAIT_V(n) asm volatile("s_waitcnt vmcnt(" #n ")" ::: "memory")
; #define PG8_WAIT_L(n) asm volatile("s_waitcnt lgkmcnt(" #n ")" ::: "memory")
; #define PG8_BAR __builtin_amdgcn_s_barrier()
; #define PG8_SCHED __builtin_amdgcn_sched_barrier(0)
; template <class Epi, class Sched>
; __device__ __forceinline__ void gemm_phase(LAS unsigned char* lds, const Gemm g, const Sched& S, const Epi& E) {
;     ...
;             PG8_LDB(B0, 0, 0); PG8_LDB(B1, 0, 1); PG8_SCHED; PG8_LDA(At, 0, 0); PG8_STAGE(PG8_SA(1, 1), a1 + hstep, voffA);
;             PG8_WAIT_V(8); PG8_WAIT_L(0); PG8_BAR; PG8_MMA(0, 0, At, B0); PG8_MMA(0, 1, At, B1); PG8_BAR; PG8_SCHED;
;             PG8_LDA(At, 0, 1); PG8_STAGE(PG8_SB(0, 0), b2, voffB); PG8_STAGE(PG8_SB(0, 1), b2 + hstep, voffB); PG8_STAGE(PG8_SA(0, 0), a2, voffA);
;             PG8_WAIT_V(8); PG8_WAIT_L(0); PG8_BAR; PG8_MMA(1, 0, At, B0); PG8_MMA(1, 1, At, B1); PG8_BAR; PG8_SCHED;
.Lrot_mlp2:
	v_add_u32_e32 v154, s1, v160
	v_add_u32_e32 v158, s61, v160
	ds_read_b128 v[130:133], v154
	ds_read_b128 v[134:137], v154 offset:1024
	ds_read_b128 v[138:141], v154 offset:2048
	ds_read_b128 v[154:157], v154 offset:3072
	ds_read_b128 v[162:165], v158
	ds_read_b128 v[166:169], v158 offset:1024
	ds_read_b128 v[170:173], v158 offset:2048
	ds_read_b128 v[174:177], v158 offset:3072
	s_add_u32 s46, s46, s2
	s_addc_u32 s47, s47, s3
	s_add_u32 s46, s46, s18
	s_addc_u32 s47, s47, s19
	s_add_u32 s46, s46, 0x80
	s_addc_u32 s47, s47, 0
	s_add_i32 m0, s5, 0xc000
	ds_read_b128 v[178:181], v161
	ds_read_b128 v[182:185], v161 offset:1024
	ds_read_b128 v[192:195], v161 offset:2048
	ds_read_b128 v[196:199], v161 offset:3072
	ds_read_b128 v[200:203], v161 offset:4096
	ds_read_b128 v[204:207], v161 offset:5120
	ds_read_b128 v[208:211], v161 offset:6144
	ds_read_b128 v[212:215], v161 offset:7168
	global_load_lds_dwordx4 v146, s[46:47]
	s_add_i32 m0, s5, 0xe000
	s_nop 0
	global_load_lds_dwordx4 v144, s[46:47]
	s_waitcnt vmcnt(8)
	s_waitcnt lgkmcnt(0)
	s_barrier
	s_setprio 1
	s_waitcnt lgkmcnt(0)
	v_mfma_f32_16x16x32_bf16 v[122:125], v[130:133], v[178:181], v[122:125]
	v_mfma_f32_16x16x32_bf16 v[126:129], v[138:141], v[178:181], v[126:129]
	v_mfma_f32_16x16x32_bf16 v[110:113], v[130:133], v[192:195], v[110:113]
	v_mfma_f32_16x16x32_bf16 v[106:109], v[138:141], v[192:195], v[106:109]
	v_mfma_f32_16x16x32_bf16 v[94:97], v[130:133], v[200:203], v[94:97]
	v_mfma_f32_16x16x32_bf16 v[90:93], v[138:141], v[200:203], v[90:93]
	v_mfma_f32_16x16x32_bf16 v[78:81], v[130:133], v[208:211], v[78:81]
	v_mfma_f32_16x16x32_bf16 v[74:77], v[138:141], v[208:211], v[74:77]
	v_mfma_f32_16x16x32_bf16 v[122:125], v[134:137], v[182:185], v[122:125]
	v_mfma_f32_16x16x32_bf16 v[126:129], v[154:157], v[182:185], v[126:129]
	v_mfma_f32_16x16x32_bf16 v[110:113], v[134:137], v[196:199], v[110:113]
	v_mfma_f32_16x16x32_bf16 v[106:109], v[154:157], v[196:199], v[106:109]
	v_mfma_f32_16x16x32_bf16 v[94:97], v[134:137], v[204:207], v[94:97]
	v_mfma_f32_16x16x32_bf16 v[90:93], v[154:157], v[204:207], v[90:93]
	v_mfma_f32_16x16x32_bf16 v[78:81], v[134:137], v[212:215], v[78:81]
	v_mfma_f32_16x16x32_bf16 v[74:77], v[154:157], v[212:215], v[74:77]
	s_setprio 0
	s_setprio 1
	v_mfma_f32_16x16x32_bf16 v[118:121], v[162:165], v[178:181], v[118:121]
	v_mfma_f32_16x16x32_bf16 v[114:117], v[170:173], v[178:181], v[114:117]
	v_mfma_f32_16x16x32_bf16 v[102:105], v[162:165], v[192:195], v[102:105]
	v_mfma_f32_16x16x32_bf16 v[98:101], v[170:173], v[192:195], v[98:101]
	v_mfma_f32_16x16x32_bf16 v[86:89], v[162:165], v[200:203], v[86:89]
	v_mfma_f32_16x16x32_bf16 v[82:85], v[170:173], v[200:203], v[82:85]
	v_mfma_f32_16x16x32_bf16 v[70:73], v[162:165], v[208:211], v[70:73]
	v_mfma_f32_16x16x32_bf16 v[66:69], v[170:173], v[208:211], v[66:69]
	v_mfma_f32_16x16x32_bf16 v[118:121], v[166:169], v[182:185], v[118:121]
	v_mfma_f32_16x16x32_bf16 v[114:117], v[174:177], v[182:185], v[114:117]
	v_mfma_f32_16x16x32_bf16 v[102:105], v[166:169], v[196:199], v[102:105]
	v_mfma_f32_16x16x32_bf16 v[98:101], v[174:177], v[196:199], v[98:101]
	v_mfma_f32_16x16x32_bf16 v[86:89], v[166:169], v[204:207], v[86:89]
	v_mfma_f32_16x16x32_bf16 v[82:85], v[174:177], v[204:207], v[82:85]
	v_mfma_f32_16x16x32_bf16 v[70:73], v[166:169], v[212:215], v[70:73]
	v_mfma_f32_16x16x32_bf16 v[66:69], v[174:177], v[212:215], v[66:69]
	s_setprio 0
	s_barrier
	s_add_i32 s1, s1, s4
	s_mov_b32 m0, s1
	ds_read_b128 v[178:181], v161 offset:16384
	ds_read_b128 v[182:185], v161 offset:17408
	ds_read_b128 v[192:195], v161 offset:18432
	ds_read_b128 v[196:199], v161 offset:19456
	ds_read_b128 v[200:203], v161 offset:20480
	ds_read_b128 v[204:207], v161 offset:21504
	ds_read_b128 v[208:211], v161 offset:22528
	ds_read_b128 v[212:215], v161 offset:23552
	global_load_lds_dwordx4 v0, s[62:63]
	s_add_i32 m0, s1, 0x2000
	s_add_u32 s46, s62, s18
	s_addc_u32 s47, s63, s19
	s_add_i32 s1, s61, s4
	global_load_lds_dwordx4 v142, s[62:63]
	s_mov_b32 m0, s1
	s_nop 0
	global_load_lds_dwordx4 v0, s[46:47]
	s_add_i32 m0, s1, 0x2000
	s_nop 0
	global_load_lds_dwordx4 v142, s[46:47]
	s_mov_b32 m0, s5
	s_nop 0
	global_load_lds_dwordx4 v146, s[50:51]
	s_mov_b32 m0, s52
	s_nop 0
	global_load_lds_dwordx4 v144, s[50:51]
	s_waitcnt vmcnt(8)
	s_waitcnt lgkmcnt(0)
	s_barrier
	s_setprio 1
	s_waitcnt lgkmcnt(0)
	v_mfma_f32_16x16x32_bf16 v[62:65], v[130:133], v[178:181], v[62:65]
	v_mfma_f32_16x16x32_bf16 v[58:61], v[138:141], v[178:181], v[58:61]
	v_mfma_f32_16x16x32_bf16 v[46:49], v[130:133], v[192:195], v[46:49]
	v_mfma_f32_16x16x32_bf16 v[42:45], v[138:141], v[192:195], v[42:45]
	v_mfma_f32_16x16x32_bf16 v[30:33], v[130:133], v[200:203], v[30:33]
	v_mfma_f32_16x16x32_bf16 v[26:29], v[138:141], v[200:203], v[26:29]
	v_mfma_f32_16x16x32_bf16 v[14:17], v[130:133], v[208:211], v[14:17]
	v_mfma_f32_16x16x32_bf16 v[10:13], v[138:141], v[208:211], v[10:13]
	v_mfma_f32_16x16x32_bf16 v[62:65], v[134:137], v[182:185], v[62:65]
	v_mfma_f32_16x16x32_bf16 v[58:61], v[154:157], v[182:185], v[58:61]
	v_mfma_f32_16x16x32_bf16 v[46:49], v[134:137], v[196:199], v[46:49]
	v_mfma_f32_16x16x32_bf16 v[42:45], v[154:157], v[196:199], v[42:45]
	v_mfma_f32_16x16x32_bf16 v[30:33], v[134:137], v[204:207], v[30:33]
	v_mfma_f32_16x16x32_bf16 v[26:29], v[154:157], v[204:207], v[26:29]
	v_mfma_f32_16x16x32_bf16 v[14:17], v[134:137], v[212:215], v[14:17]
	v_mfma_f32_16x16x32_bf16 v[10:13], v[154:157], v[212:215], v[10:13]
	s_setprio 0
	s_setprio 1
	v_mfma_f32_16x16x32_bf16 v[54:57], v[162:165], v[178:181], v[54:57]
	v_mfma_f32_16x16x32_bf16 v[50:53], v[170:173], v[178:181], v[50:53]
	v_mfma_f32_16x16x32_bf16 v[38:41], v[162:165], v[192:195], v[38:41]
	v_mfma_f32_16x16x32_bf16 v[34:37], v[170:173], v[192:195], v[34:37]
	v_mfma_f32_16x16x32_bf16 v[22:25], v[162:165], v[200:203], v[22:25]
	v_mfma_f32_16x16x32_bf16 v[18:21], v[170:173], v[200:203], v[18:21]
	v_mfma_f32_16x16x32_bf16 v[6:9], v[162:165], v[208:211], v[6:9]
	v_mfma_f32_16x16x32_bf16 v[2:5], v[170:173], v[208:211], v[2:5]
	v_mfma_f32_16x16x32_bf16 v[54:57], v[166:169], v[182:185], v[54:57]
	v_mfma_f32_16x16x32_bf16 v[50:53], v[174:177], v[182:185], v[50:53]
	v_mfma_f32_16x16x32_bf16 v[38:41], v[166:169], v[196:199], v[38:41]
	v_mfma_f32_16x16x32_bf16 v[34:37], v[174:177], v[196:199], v[34:37]
	v_mfma_f32_16x16x32_bf16 v[22:25], v[166:169], v[204:207], v[22:25]
	v_mfma_f32_16x16x32_bf16 v[18:21], v[174:177], v[204:207], v[18:21]
	v_mfma_f32_16x16x32_bf16 v[6:9], v[166:169], v[212:215], v[6:9]
	v_mfma_f32_16x16x32_bf16 v[2:5], v[174:177], v[212:215], v[2:5]
	s_setprio 0
	s_barrier
; #define PG8_STAGE(bufoff, gbase, voff) do { _Pragma("unroll") for (int _i = 0; _i < 2; ++_i) \
;         __builtin_amdgcn_global_load_lds((const unsigned*)((const char*)(gbase) + (voff)[_i]), (LAS unsigned*)(lds + (bufoff) + ldsw + _i * 8192), 16, 0, 0); } while (0)
; #define PG8_LDA(dst, b, h) do { _Pragma("unroll") for (int m = 0; m < 4; ++m) _Pragma("unroll") for (int k = 0; k < 2; ++k) dst[m][k] = *(const LAS bf16x8*)(lds + PG8_SA(b, h) + aoff + m * 2048 + k * 1024); } while (0)
; #define PG8_LDB(dst, b, h) do { _Pragma("unroll") for (int n = 0; n < 2; ++n) _Pragma("unroll") for (int k = 0; k < 2; ++k) dst[n][k] = *(const LAS bf16x8*)(lds + PG8_SB(b, h) + boff + n * 2048 + k * 1024); } while (0)
; #define PG8_MMA(ai, bj, At, Bt) do { __builtin_amdgcn_s_setprio(1); _Pragma("unroll") for (int m = 0; m < 4; ++m) _Pragma("unroll") for (int n = 0; n < 2; ++n) _Pragma("unroll") for (int k = 0; k < 2; ++k) \
;         acc[ai][bj][m][n] = __builtin_amdgcn_mfma_f32_16x16x32_bf16(Bt[n][k], At[m][k], acc[ai][bj][m][n], 0, 0, 0); __builtin_amdgcn_s_setprio(0); } while (0)
; #define PG8_WAIT_V(n) asm volatile("s_waitcnt vmcnt(" #n ")" ::: "memory")
; #define PG8_WAIT_L(n) asm volatile("s_waitcnt lgkmcnt(" #n ")" ::: "memory")
; #define PG8_BAR __builtin_amdgcn_s_barrier()
; #define PG8_SCHED __builtin_amdgcn_sched_barrier(0)
; template <class Epi, class Sched>
; __device__ __forceinline__ void gemm_phase(LAS unsigned char* lds, const Gemm g, const Sched& S, const Epi& E) {
;     ...
;             PG8_LDB(B0, 1, 0); PG8_LDB(B1, 1, 1); PG8_SCHED; PG8_LDA(At, 1, 0); PG8_STAGE(PG8_SA(0, 1), a2 + hstep, voffA);
;             PG8_WAIT_V(8); PG8_WAIT_L(0); PG8_BAR; PG8_MMA(0, 0, At, B0); PG8_MMA(0, 1, At, B1); PG8_BAR; PG8_SCHED;
	s_add_i32 s1, 0, 0x18000
	s_add_i32 s61, 0, 0x1c000
	v_add_u32_e32 v154, s1, v160
	v_add_u32_e32 v174, s61, v160
	ds_read_b128 v[130:133], v154
	ds_read_b128 v[134:137], v154 offset:1024
	ds_read_b128 v[138:141], v154 offset:2048
	ds_read_b128 v[154:157], v154 offset:3072
	ds_read_b128 v[162:165], v174
	ds_read_b128 v[166:169], v174 offset:1024
	ds_read_b128 v[170:173], v174 offset:2048
	ds_read_b128 v[174:177], v174 offset:3072
	s_add_u32 s46, s50, s18
	s_addc_u32 s47, s51, s19
	s_mov_b32 m0, s53
	ds_read_b128 v[178:181], v161 offset:32768
	ds_read_b128 v[182:185], v161 offset:33792
	ds_read_b128 v[192:195], v161 offset:34816
	ds_read_b128 v[196:199], v161 offset:35840
	ds_read_b128 v[200:203], v161 offset:36864
	ds_read_b128 v[204:207], v161 offset:37888
	ds_read_b128 v[208:211], v161 offset:38912
	ds_read_b128 v[212:215], v161 offset:39936
	global_load_lds_dwordx4 v146, s[46:47]
	s_mov_b32 m0, s54
	s_nop 0
	global_load_lds_dwordx4 v144, s[46:47]
	s_waitcnt vmcnt(8)
	s_waitcnt lgkmcnt(0)
	s_barrier
	s_setprio 1
	s_waitcnt lgkmcnt(0)
	v_mfma_f32_16x16x32_bf16 v[122:125], v[130:133], v[178:181], v[122:125]
	v_mfma_f32_16x16x32_bf16 v[126:129], v[138:141], v[178:181], v[126:129]
	v_mfma_f32_16x16x32_bf16 v[110:113], v[130:133], v[192:195], v[110:113]
	v_mfma_f32_16x16x32_bf16 v[106:109], v[138:141], v[192:195], v[106:109]
	v_mfma_f32_16x16x32_bf16 v[94:97], v[130:133], v[200:203], v[94:97]
	v_mfma_f32_16x16x32_bf16 v[90:93], v[138:141], v[200:203], v[90:93]
	v_mfma_f32_16x16x32_bf16 v[78:81], v[130:133], v[208:211], v[78:81]
	v_mfma_f32_16x16x32_bf16 v[74:77], v[138:141], v[208:211], v[74:77]
	v_mfma_f32_16x16x32_bf16 v[122:125], v[134:137], v[182:185], v[122:125]
	v_mfma_f32_16x16x32_bf16 v[126:129], v[154:157], v[182:185], v[126:129]
	v_mfma_f32_16x16x32_bf16 v[110:113], v[134:137], v[196:199], v[110:113]
	v_mfma_f32_16x16x32_bf16 v[106:109], v[154:157], v[196:199], v[106:109]
	v_mfma_f32_16x16x32_bf16 v[94:97], v[134:137], v[204:207], v[94:97]
	v_mfma_f32_16x16x32_bf16 v[90:93], v[154:157], v[204:207], v[90:93]
	v_mfma_f32_16x16x32_bf16 v[78:81], v[134:137], v[212:215], v[78:81]
	v_mfma_f32_16x16x32_bf16 v[74:77], v[154:157], v[212:215], v[74:77]
	s_setprio 0
	s_setprio 1
	v_mfma_f32_16x16x32_bf16 v[118:121], v[162:165], v[178:181], v[118:121]
	v_mfma_f32_16x16x32_bf16 v[114:117], v[170:173], v[178:181], v[114:117]
	v_mfma_f32_16x16x32_bf16 v[102:105], v[162:165], v[192:195], v[102:105]
	v_mfma_f32_16x16x32_bf16 v[98:101], v[170:173], v[192:195], v[98:101]
	v_mfma_f32_16x16x32_bf16 v[86:89], v[162:165], v[200:203], v[86:89]
	v_mfma_f32_16x16x32_bf16 v[82:85], v[170:173], v[200:203], v[82:85]
	v_mfma_f32_16x16x32_bf16 v[70:73], v[162:165], v[208:211], v[70:73]
	v_mfma_f32_16x16x32_bf16 v[66:69], v[170:173], v[208:211], v[66:69]
	v_mfma_f32_16x16x32_bf16 v[118:121], v[166:169], v[182:185], v[118:121]
	v_mfma_f32_16x16x32_bf16 v[114:117], v[174:177], v[182:185], v[114:117]
	v_mfma_f32_16x16x32_bf16 v[102:105], v[166:169], v[196:199], v[102:105]
	v_mfma_f32_16x16x32_bf16 v[98:101], v[174:177], v[196:199], v[98:101]
	v_mfma_f32_16x16x32_bf16 v[86:89], v[166:169], v[204:207], v[86:89]
	v_mfma_f32_16x16x32_bf16 v[82:85], v[174:177], v[204:207], v[82:85]
	v_mfma_f32_16x16x32_bf16 v[70:73], v[166:169], v[212:215], v[70:73]
	v_mfma_f32_16x16x32_bf16 v[66:69], v[174:177], v[212:215], v[66:69]
	s_setprio 0
	s_barrier
; #define PG8_STAGE(bufoff, gbase, voff) do { _Pragma("unroll") for (int _i = 0; _i < 2; ++_i) \
;         __builtin_amdgcn_global_load_lds((const unsigned*)((const char*)(gbase) + (voff)[_i]), (LAS unsigned*)(lds + (bufoff) + ldsw + _i * 8192), 16, 0, 0); } while (0)
; #define PG8_LDA(dst, b, h) do { _Pragma("unroll") for (int m = 0; m < 4; ++m) _Pragma("unroll") for (int k = 0; k < 2; ++k) dst[m][k] = *(const LAS bf16x8*)(lds + PG8_SA(b, h) + aoff + m * 2048 + k * 1024); } while (0)
; #define PG8_MMA(ai, bj, At, Bt) do { __builtin_amdgcn_s_setprio(1); _Pragma("unroll") for (int m = 0; m < 4; ++m) _Pragma("unroll") for (int n = 0; n < 2; ++n) _Pragma("unroll") for (int k = 0; k < 2; ++k) \
;         acc[ai][bj][m][n] = __builtin_amdgcn_mfma_f32_16x16x32_bf16(Bt[n][k], At[m][k], acc[ai][bj][m][n], 0, 0, 0); __builtin_amdgcn_s_setprio(0); } while (0)
; #define PG8_WAIT_V(n) asm volatile("s_waitcnt vmcnt(" #n ")" ::: "memory")
; #define PG8_WAIT_L(n) asm volatile("s_waitcnt lgkmcnt(" #n ")" ::: "memory")
; #define PG8_BAR __builtin_amdgcn_s_barrier()
; #define PG8_SCHED __builtin_amdgcn_sched_barrier(0)
; template <class Epi, class Sched>
; __device__ __forceinline__ void gemm_phase(LAS unsigned char* lds, const Gemm g, const Sched& S, const Epi& E) {
;     ...
;         for (int t = 0; t < nt; t += 2) {
;             const bool last = (t == nt - 2);
;             const char* a1 = cA + (size_t)(t + 1) * kstep;
;             const char* a2 = last ? nA : cA + (size_t)(t + 2) * kstep; const char* b2 = last ? nB : cB + (size_t)(t + 2) * kstep;
;             const char* a3 = a2 + kstep; const char* b3 = b2 + kstep;
;     ...
;             PG8_LDA(At, 1, 1); PG8_STAGE(PG8_SB(1, 0), b3, voffB); PG8_STAGE(PG8_SB(1, 1), b3 + hstep, voffB); PG8_STAGE(PG8_SA(1, 0), a3, voffA);
;             PG8_WAIT_V(8); PG8_WAIT_L(0); PG8_BAR; PG8_MMA(1, 0, At, B0); PG8_MMA(1, 1, At, B1); PG8_BAR; PG8_SCHED;
	s_add_i32 s1, s1, s4
	s_add_u32 s46, s62, 0x80
	s_addc_u32 s47, s63, 0
	s_mov_b32 m0, s1
	ds_read_b128 v[178:181], v161 offset:49152
	ds_read_b128 v[182:185], v161 offset:50176
	ds_read_b128 v[192:195], v161 offset:51200
	ds_read_b128 v[196:199], v161 offset:52224
	ds_read_b128 v[200:203], v161 offset:53248
	ds_read_b128 v[204:207], v161 offset:54272
	ds_read_b128 v[208:211], v161 offset:55296
	ds_read_b128 v[212:215], v161 offset:56320
	global_load_lds_dwordx4 v0, s[46:47]
	s_add_i32 m0, s1, 0x2000
	s_add_i32 s1, s61, s4
	global_load_lds_dwordx4 v142, s[46:47]
	s_add_u32 s46, s46, s18
	s_addc_u32 s47, s47, s19
	s_mov_b32 m0, s1
	s_nop 0
	global_load_lds_dwordx4 v0, s[46:47]
	s_add_i32 m0, s1, 0x2000
	s_nop 0
	global_load_lds_dwordx4 v142, s[46:47]
	s_add_u32 s46, s50, 0x80
	s_addc_u32 s47, s51, 0
	s_mov_b32 m0, s55
	s_nop 0
	global_load_lds_dwordx4 v146, s[46:47]
	s_mov_b32 m0, s56
	s_nop 0
	global_load_lds_dwordx4 v144, s[46:47]
	s_waitcnt vmcnt(8)
	s_waitcnt lgkmcnt(0)
	s_barrier
	s_setprio 1
	s_waitcnt lgkmcnt(0)
	v_mfma_f32_16x16x32_bf16 v[62:65], v[130:133], v[178:181], v[62:65]
	v_mfma_f32_16x16x32_bf16 v[58:61], v[138:141], v[178:181], v[58:61]
	v_mfma_f32_16x16x32_bf16 v[46:49], v[130:133], v[192:195], v[46:49]
	v_mfma_f32_16x16x32_bf16 v[42:45], v[138:141], v[192:195], v[42:45]
	v_mfma_f32_16x16x32_bf16 v[30:33], v[130:133], v[200:203], v[30:33]
	v_mfma_f32_16x16x32_bf16 v[26:29], v[138:141], v[200:203], v[26:29]
	v_mfma_f32_16x16x32_bf16 v[14:17], v[130:133], v[208:211], v[14:17]
	v_mfma_f32_16x16x32_bf16 v[10:13], v[138:141], v[208:211], v[10:13]
	v_mfma_f32_16x16x32_bf16 v[62:65], v[134:137], v[182:185], v[62:65]
	v_mfma_f32_16x16x32_bf16 v[58:61], v[154:157], v[182:185], v[58:61]
	v_mfma_f32_16x16x32_bf16 v[46:49], v[134:137], v[196:199], v[46:49]
	v_mfma_f32_16x16x32_bf16 v[42:45], v[154:157], v[196:199], v[42:45]
	v_mfma_f32_16x16x32_bf16 v[30:33], v[134:137], v[204:207], v[30:33]
	v_mfma_f32_16x16x32_bf16 v[26:29], v[154:157], v[204:207], v[26:29]
	v_mfma_f32_16x16x32_bf16 v[14:17], v[134:137], v[212:215], v[14:17]
	v_mfma_f32_16x16x32_bf16 v[10:13], v[154:157], v[212:215], v[10:13]
	s_setprio 0
	s_setprio 1
	v_mfma_f32_16x16x32_bf16 v[54:57], v[162:165], v[178:181], v[54:57]
	v_mfma_f32_16x16x32_bf16 v[50:53], v[170:173], v[178:181], v[50:53]
	v_mfma_f32_16x16x32_bf16 v[38:41], v[162:165], v[192:195], v[38:41]
	v_mfma_f32_16x16x32_bf16 v[34:37], v[170:173], v[192:195], v[34:37]
	v_mfma_f32_16x16x32_bf16 v[22:25], v[162:165], v[200:203], v[22:25]
	v_mfma_f32_16x16x32_bf16 v[18:21], v[170:173], v[200:203], v[18:21]
	v_mfma_f32_16x16x32_bf16 v[6:9], v[162:165], v[208:211], v[6:9]
	v_mfma_f32_16x16x32_bf16 v[2:5], v[170:173], v[208:211], v[2:5]
	v_mfma_f32_16x16x32_bf16 v[54:57], v[166:169], v[182:185], v[54:57]
	v_mfma_f32_16x16x32_bf16 v[50:53], v[174:177], v[182:185], v[50:53]
	v_mfma_f32_16x16x32_bf16 v[38:41], v[166:169], v[196:199], v[38:41]
	v_mfma_f32_16x16x32_bf16 v[34:37], v[174:177], v[196:199], v[34:37]
	v_mfma_f32_16x16x32_bf16 v[22:25], v[166:169], v[204:207], v[22:25]
	v_mfma_f32_16x16x32_bf16 v[18:21], v[174:177], v[204:207], v[18:21]
	v_mfma_f32_16x16x32_bf16 v[6:9], v[166:169], v[212:215], v[6:9]
	v_mfma_f32_16x16x32_bf16 v[2:5], v[174:177], v[212:215], v[2:5]
	s_setprio 0
	s_mov_b32 s99, s60
	s_mov_b64 s[46:47], s[48:49]
	s_mov_b32 s50, s60
	s_add_i32 s60, s50, 2
	s_add_u32 s48, s46, 0x100
	s_addc_u32 s49, s47, 0
	s_add_u32 s1, s9, s46
	s_addc_u32 s51, s36, s47
	s_cmp_eq_u32 s58, s50
	s_cselect_b32 s50, 0xff000000, s48
	s_cselect_b32 s61, -1, s49
	s_cselect_b32 s62, s44, s1
	s_cselect_b32 s63, s45, s51
	s_add_u32 s50, s2, s50
	s_addc_u32 s51, s3, s61
	s_add_i32 s1, 0, 0x10000
	s_add_i32 s61, 0, 0x14000
	s_cmp_ge_i32 s99, s57
	s_barrier
	s_cbranch_scc0 .Lrot_mlp2
